# static prio for waves 4-7 + K-loops of GEMM1/DFT/DFTc/branch restructured to 4 double-length phases (32 MFMA per barrier handoff, reads of B1 hoisted, even-phase DMA after the barrier)
# speedup vs baseline: 1.0239x; 1.0076x over previous
.LBB0_112:
	v_or_b32_e32 v100, 0x10000, v244
	v_add_u32_e32 v104, 0x10400, v244
	v_add_u32_e32 v116, 0x10800, v244
	v_add_u32_e32 v120, 0x10c00, v244
	s_add_i32 s45, s28, 2
	ds_read_b128 v[100:103], v100
	ds_read_b128 v[104:107], v104
	ds_read_b128 v[116:119], v116
	ds_read_b128 v[120:123], v120
	s_add_u32 s29, s22, 0xfffc0080
	s_addc_u32 s30, s23, -1
	s_cmp_eq_u32 s68, s28
	s_cselect_b32 s28, s37, s38
	s_cselect_b32 s31, s27, s30
	s_cselect_b32 s30, s33, s29
	s_cselect_b32 s29, s36, s39
	v_lshl_add_u64 v[176:177], s[22:23], 0, v[194:195]
	s_add_i32 m0, s59, 0xc000
	ds_read_b128 v[132:135], v243
	ds_read_b128 v[140:143], v243 offset:1024
	ds_read_b128 v[152:155], v243 offset:2048
	ds_read_b128 v[156:159], v243 offset:3072
	ds_read_b128 v[160:163], v243 offset:4096
	ds_read_b128 v[164:167], v243 offset:5120
	ds_read_b128 v[168:171], v243 offset:6144
	ds_read_b128 v[172:175], v243 offset:7168
	global_load_lds_dwordx4 v[176:177], off
	v_lshl_add_u64 v[176:177], s[22:23], 0, v[196:197]
	s_add_i32 m0, s59, 0xe000
	s_nop 0
	global_load_lds_dwordx4 v[176:177], off
	v_or_b32_e32 v176, 0x14000, v244
	v_add_u32_e32 v180, 0x14400, v244
	v_add_u32_e32 v198, 0x14800, v244
	v_add_u32_e32 v202, 0x14c00, v244
	ds_read_b128 v[176:179], v176
	ds_read_b128 v[180:183], v180
	ds_read_b128 v[198:201], v198
	ds_read_b128 v[202:205], v202
	s_waitcnt vmcnt(8) lgkmcnt(0)
	s_barrier
	v_mfma_f32_16x16x32_bf16 v[148:151], v[100:103], v[132:135], v[148:151]
	v_mfma_f32_16x16x32_bf16 v[144:147], v[116:119], v[132:135], v[144:147]
	v_mfma_f32_16x16x32_bf16 v[136:139], v[100:103], v[152:155], v[136:139]
	v_mfma_f32_16x16x32_bf16 v[128:131], v[116:119], v[152:155], v[128:131]
	v_mfma_f32_16x16x32_bf16 v[124:127], v[100:103], v[160:163], v[124:127]
	v_mfma_f32_16x16x32_bf16 v[112:115], v[116:119], v[160:163], v[112:115]
	v_mfma_f32_16x16x32_bf16 v[108:111], v[100:103], v[168:171], v[108:111]
	v_mfma_f32_16x16x32_bf16 v[96:99], v[116:119], v[168:171], v[96:99]
	v_mfma_f32_16x16x32_bf16 v[148:151], v[104:107], v[140:143], v[148:151]
	v_mfma_f32_16x16x32_bf16 v[144:147], v[120:123], v[140:143], v[144:147]
	v_mfma_f32_16x16x32_bf16 v[136:139], v[104:107], v[156:159], v[136:139]
	v_mfma_f32_16x16x32_bf16 v[128:131], v[120:123], v[156:159], v[128:131]
	v_mfma_f32_16x16x32_bf16 v[124:127], v[104:107], v[164:167], v[124:127]
	v_mfma_f32_16x16x32_bf16 v[112:115], v[120:123], v[164:167], v[112:115]
	v_mfma_f32_16x16x32_bf16 v[108:111], v[104:107], v[172:175], v[108:111]
	v_mfma_f32_16x16x32_bf16 v[96:99], v[120:123], v[172:175], v[96:99]
	v_mfma_f32_16x16x32_bf16 v[92:95], v[176:179], v[132:135], v[92:95]
	v_mfma_f32_16x16x32_bf16 v[88:91], v[198:201], v[132:135], v[88:91]
	v_mfma_f32_16x16x32_bf16 v[84:87], v[176:179], v[152:155], v[84:87]
	v_mfma_f32_16x16x32_bf16 v[80:83], v[198:201], v[152:155], v[80:83]
	v_mfma_f32_16x16x32_bf16 v[76:79], v[176:179], v[160:163], v[76:79]
	v_mfma_f32_16x16x32_bf16 v[72:75], v[198:201], v[160:163], v[72:75]
	v_mfma_f32_16x16x32_bf16 v[68:71], v[176:179], v[168:171], v[68:71]
	v_mfma_f32_16x16x32_bf16 v[64:67], v[198:201], v[168:171], v[64:67]
	v_mfma_f32_16x16x32_bf16 v[92:95], v[180:183], v[140:143], v[92:95]
	v_mfma_f32_16x16x32_bf16 v[88:91], v[202:205], v[140:143], v[88:91]
	v_mfma_f32_16x16x32_bf16 v[84:87], v[180:183], v[156:159], v[84:87]
	v_mfma_f32_16x16x32_bf16 v[80:83], v[202:205], v[156:159], v[80:83]
	v_mfma_f32_16x16x32_bf16 v[76:79], v[180:183], v[164:167], v[76:79]
	v_mfma_f32_16x16x32_bf16 v[72:75], v[202:205], v[164:167], v[72:75]
	v_mfma_f32_16x16x32_bf16 v[68:71], v[180:183], v[172:175], v[68:71]
	v_mfma_f32_16x16x32_bf16 v[64:67], v[202:205], v[172:175], v[64:67]
	s_barrier
	s_mov_b32 m0, s53
	v_lshl_add_u64 v[206:207], s[28:29], 0, v[184:185]
	global_load_lds_dwordx4 v[206:207], off
	v_lshl_add_u64 v[208:209], s[28:29], 0, v[190:191]
	s_mov_b32 m0, s60
	s_nop 0
	global_load_lds_dwordx4 v[208:209], off
	s_mov_b32 m0, s59
	v_lshl_add_u64 v[210:211], s[30:31], 0, v[186:187]
	ds_read_b128 v[132:135], v243 offset:16384
	ds_read_b128 v[140:143], v243 offset:17408
	ds_read_b128 v[152:155], v243 offset:18432
	ds_read_b128 v[156:159], v243 offset:19456
	ds_read_b128 v[160:163], v243 offset:20480
	ds_read_b128 v[164:167], v243 offset:21504
	ds_read_b128 v[168:171], v243 offset:22528
	ds_read_b128 v[172:175], v243 offset:23552
	global_load_lds_dwordx4 v[210:211], off
	v_lshl_add_u64 v[212:213], s[30:31], 0, v[188:189]
	s_mov_b32 m0, s61
	s_nop 0
	global_load_lds_dwordx4 v[212:213], off
	s_waitcnt vmcnt(6) lgkmcnt(0)
	s_barrier
	v_mfma_f32_16x16x32_bf16 v[60:63], v[100:103], v[132:135], v[60:63]
	v_mfma_f32_16x16x32_bf16 v[56:59], v[116:119], v[132:135], v[56:59]
	v_mfma_f32_16x16x32_bf16 v[52:55], v[100:103], v[152:155], v[52:55]
	v_mfma_f32_16x16x32_bf16 v[48:51], v[116:119], v[152:155], v[48:51]
	v_mfma_f32_16x16x32_bf16 v[44:47], v[100:103], v[160:163], v[44:47]
	v_mfma_f32_16x16x32_bf16 v[40:43], v[116:119], v[160:163], v[40:43]
	v_mfma_f32_16x16x32_bf16 v[36:39], v[100:103], v[168:171], v[36:39]
	v_mfma_f32_16x16x32_bf16 v[32:35], v[116:119], v[168:171], v[32:35]
	v_mfma_f32_16x16x32_bf16 v[60:63], v[104:107], v[140:143], v[60:63]
	v_mfma_f32_16x16x32_bf16 v[56:59], v[120:123], v[140:143], v[56:59]
	v_mfma_f32_16x16x32_bf16 v[52:55], v[104:107], v[156:159], v[52:55]
	v_mfma_f32_16x16x32_bf16 v[48:51], v[120:123], v[156:159], v[48:51]
	v_mfma_f32_16x16x32_bf16 v[44:47], v[104:107], v[164:167], v[44:47]
	v_mfma_f32_16x16x32_bf16 v[40:43], v[120:123], v[164:167], v[40:43]
	v_mfma_f32_16x16x32_bf16 v[36:39], v[104:107], v[172:175], v[36:39]
	v_mfma_f32_16x16x32_bf16 v[32:35], v[120:123], v[172:175], v[32:35]
	v_mfma_f32_16x16x32_bf16 v[28:31], v[176:179], v[132:135], v[28:31]
	v_mfma_f32_16x16x32_bf16 v[24:27], v[198:201], v[132:135], v[24:27]
	v_mfma_f32_16x16x32_bf16 v[20:23], v[176:179], v[152:155], v[20:23]
	v_mfma_f32_16x16x32_bf16 v[16:19], v[198:201], v[152:155], v[16:19]
	v_mfma_f32_16x16x32_bf16 v[12:15], v[176:179], v[160:163], v[12:15]
	v_mfma_f32_16x16x32_bf16 v[4:7], v[198:201], v[160:163], v[4:7]
	v_mfma_f32_16x16x32_bf16 v[8:11], v[176:179], v[168:171], v[8:11]
	v_mfma_f32_16x16x32_bf16 v[0:3], v[198:201], v[168:171], v[0:3]
	v_mfma_f32_16x16x32_bf16 v[28:31], v[180:183], v[140:143], v[28:31]
	v_mfma_f32_16x16x32_bf16 v[24:27], v[202:205], v[140:143], v[24:27]
	v_mfma_f32_16x16x32_bf16 v[20:23], v[180:183], v[156:159], v[20:23]
	v_mfma_f32_16x16x32_bf16 v[16:19], v[202:205], v[156:159], v[16:19]
	v_mfma_f32_16x16x32_bf16 v[12:15], v[180:183], v[164:167], v[12:15]
	v_mfma_f32_16x16x32_bf16 v[4:7], v[202:205], v[164:167], v[4:7]
	v_mfma_f32_16x16x32_bf16 v[8:11], v[180:183], v[172:175], v[8:11]
	v_mfma_f32_16x16x32_bf16 v[0:3], v[202:205], v[172:175], v[0:3]
	s_barrier
	s_add_u32 s66, s28, 0x10000
	s_addc_u32 s67, s29, 0
	s_mov_b32 m0, s62
	v_lshl_add_u64 v[100:101], s[66:67], 0, v[184:185]
	global_load_lds_dwordx4 v[100:101], off
	v_lshl_add_u64 v[100:101], s[66:67], 0, v[190:191]
	s_mov_b32 m0, s63
	s_nop 0
	global_load_lds_dwordx4 v[100:101], off
	v_or_b32_e32 v100, 0x18000, v244
	v_add_u32_e32 v104, 0x18400, v244
	v_add_u32_e32 v116, 0x18800, v244
	v_add_u32_e32 v120, 0x18c00, v244
	ds_read_b128 v[100:103], v100
	ds_read_b128 v[104:107], v104
	ds_read_b128 v[116:119], v116
	ds_read_b128 v[120:123], v120
	s_add_u32 s30, s30, 0x40000
	s_addc_u32 s31, s31, 0
	s_mov_b32 m0, s64
	v_lshl_add_u64 v[176:177], s[30:31], 0, v[186:187]
	ds_read_b128 v[132:135], v243 offset:32768
	ds_read_b128 v[140:143], v243 offset:33792
	ds_read_b128 v[152:155], v243 offset:34816
	ds_read_b128 v[156:159], v243 offset:35840
	ds_read_b128 v[160:163], v243 offset:36864
	ds_read_b128 v[164:167], v243 offset:37888
	ds_read_b128 v[168:171], v243 offset:38912
	ds_read_b128 v[172:175], v243 offset:39936
	global_load_lds_dwordx4 v[176:177], off
	v_lshl_add_u64 v[176:177], s[30:31], 0, v[188:189]
	s_mov_b32 m0, s65
	s_nop 0
	global_load_lds_dwordx4 v[176:177], off
	v_or_b32_e32 v176, 0x1c000, v244
	v_add_u32_e32 v180, 0x1c400, v244
	v_add_u32_e32 v198, 0x1c800, v244
	v_add_u32_e32 v202, 0x1cc00, v244
	ds_read_b128 v[176:179], v176
	ds_read_b128 v[180:183], v180
	ds_read_b128 v[198:201], v198
	ds_read_b128 v[202:205], v202
	s_waitcnt vmcnt(8) lgkmcnt(0)
	s_barrier
	v_mfma_f32_16x16x32_bf16 v[148:151], v[100:103], v[132:135], v[148:151]
	v_mfma_f32_16x16x32_bf16 v[144:147], v[116:119], v[132:135], v[144:147]
	v_mfma_f32_16x16x32_bf16 v[136:139], v[100:103], v[152:155], v[136:139]
	v_mfma_f32_16x16x32_bf16 v[128:131], v[116:119], v[152:155], v[128:131]
	v_mfma_f32_16x16x32_bf16 v[124:127], v[100:103], v[160:163], v[124:127]
	v_mfma_f32_16x16x32_bf16 v[112:115], v[116:119], v[160:163], v[112:115]
	v_mfma_f32_16x16x32_bf16 v[108:111], v[100:103], v[168:171], v[108:111]
	v_mfma_f32_16x16x32_bf16 v[96:99], v[116:119], v[168:171], v[96:99]
	v_mfma_f32_16x16x32_bf16 v[148:151], v[104:107], v[140:143], v[148:151]
	v_mfma_f32_16x16x32_bf16 v[144:147], v[120:123], v[140:143], v[144:147]
	v_mfma_f32_16x16x32_bf16 v[136:139], v[104:107], v[156:159], v[136:139]
	v_mfma_f32_16x16x32_bf16 v[128:131], v[120:123], v[156:159], v[128:131]
	v_mfma_f32_16x16x32_bf16 v[124:127], v[104:107], v[164:167], v[124:127]
	v_mfma_f32_16x16x32_bf16 v[112:115], v[120:123], v[164:167], v[112:115]
	v_mfma_f32_16x16x32_bf16 v[108:111], v[104:107], v[172:175], v[108:111]
	v_mfma_f32_16x16x32_bf16 v[96:99], v[120:123], v[172:175], v[96:99]
	v_mfma_f32_16x16x32_bf16 v[92:95], v[176:179], v[132:135], v[92:95]
	v_mfma_f32_16x16x32_bf16 v[88:91], v[198:201], v[132:135], v[88:91]
	v_mfma_f32_16x16x32_bf16 v[84:87], v[176:179], v[152:155], v[84:87]
	v_mfma_f32_16x16x32_bf16 v[80:83], v[198:201], v[152:155], v[80:83]
	v_mfma_f32_16x16x32_bf16 v[76:79], v[176:179], v[160:163], v[76:79]
	v_mfma_f32_16x16x32_bf16 v[72:75], v[198:201], v[160:163], v[72:75]
	v_mfma_f32_16x16x32_bf16 v[68:71], v[176:179], v[168:171], v[68:71]
	v_mfma_f32_16x16x32_bf16 v[64:67], v[198:201], v[168:171], v[64:67]
	v_mfma_f32_16x16x32_bf16 v[92:95], v[180:183], v[140:143], v[92:95]
	v_mfma_f32_16x16x32_bf16 v[88:91], v[202:205], v[140:143], v[88:91]
	v_mfma_f32_16x16x32_bf16 v[84:87], v[180:183], v[156:159], v[84:87]
	v_mfma_f32_16x16x32_bf16 v[80:83], v[202:205], v[156:159], v[80:83]
	v_mfma_f32_16x16x32_bf16 v[76:79], v[180:183], v[164:167], v[76:79]
	v_mfma_f32_16x16x32_bf16 v[72:75], v[202:205], v[164:167], v[72:75]
	v_mfma_f32_16x16x32_bf16 v[68:71], v[180:183], v[172:175], v[68:71]
	v_mfma_f32_16x16x32_bf16 v[64:67], v[202:205], v[172:175], v[64:67]
	s_barrier
	s_mov_b32 m0, s69
	v_lshl_add_u64 v[206:207], v[206:207], 0, s[24:25]
	global_load_lds_dwordx4 v[206:207], off
	v_lshl_add_u64 v[206:207], v[208:209], 0, s[24:25]
	s_mov_b32 m0, s70
	s_nop 0
	global_load_lds_dwordx4 v[206:207], off
	s_mov_b32 m0, s71
	v_lshl_add_u64 v[206:207], v[210:211], 0, s[24:25]
	ds_read_b128 v[132:135], v243 offset:49152
	ds_read_b128 v[140:143], v243 offset:50176
	ds_read_b128 v[152:155], v243 offset:51200
	ds_read_b128 v[156:159], v243 offset:52224
	ds_read_b128 v[160:163], v243 offset:53248
	ds_read_b128 v[164:167], v243 offset:54272
	ds_read_b128 v[168:171], v243 offset:55296
	ds_read_b128 v[172:175], v243 offset:56320
	global_load_lds_dwordx4 v[206:207], off
	v_lshl_add_u64 v[206:207], v[212:213], 0, s[24:25]
	s_mov_b32 m0, s54
	s_nop 0
	global_load_lds_dwordx4 v[206:207], off
	s_waitcnt vmcnt(6) lgkmcnt(0)
	s_barrier
	v_mfma_f32_16x16x32_bf16 v[60:63], v[100:103], v[132:135], v[60:63]
	v_mfma_f32_16x16x32_bf16 v[56:59], v[116:119], v[132:135], v[56:59]
	v_mfma_f32_16x16x32_bf16 v[52:55], v[100:103], v[152:155], v[52:55]
	v_mfma_f32_16x16x32_bf16 v[48:51], v[116:119], v[152:155], v[48:51]
	v_mfma_f32_16x16x32_bf16 v[44:47], v[100:103], v[160:163], v[44:47]
	v_mfma_f32_16x16x32_bf16 v[40:43], v[116:119], v[160:163], v[40:43]
	v_mfma_f32_16x16x32_bf16 v[36:39], v[100:103], v[168:171], v[36:39]
	v_mfma_f32_16x16x32_bf16 v[32:35], v[116:119], v[168:171], v[32:35]
	v_mfma_f32_16x16x32_bf16 v[60:63], v[104:107], v[140:143], v[60:63]
	v_mfma_f32_16x16x32_bf16 v[56:59], v[120:123], v[140:143], v[56:59]
	v_mfma_f32_16x16x32_bf16 v[52:55], v[104:107], v[156:159], v[52:55]
	v_mfma_f32_16x16x32_bf16 v[48:51], v[120:123], v[156:159], v[48:51]
	v_mfma_f32_16x16x32_bf16 v[44:47], v[104:107], v[164:167], v[44:47]
	v_mfma_f32_16x16x32_bf16 v[40:43], v[120:123], v[164:167], v[40:43]
	v_mfma_f32_16x16x32_bf16 v[36:39], v[104:107], v[172:175], v[36:39]
	v_mfma_f32_16x16x32_bf16 v[32:35], v[120:123], v[172:175], v[32:35]
	v_mfma_f32_16x16x32_bf16 v[28:31], v[176:179], v[132:135], v[28:31]
	v_mfma_f32_16x16x32_bf16 v[24:27], v[198:201], v[132:135], v[24:27]
	v_mfma_f32_16x16x32_bf16 v[20:23], v[176:179], v[152:155], v[20:23]
	v_mfma_f32_16x16x32_bf16 v[16:19], v[198:201], v[152:155], v[16:19]
	v_mfma_f32_16x16x32_bf16 v[12:15], v[176:179], v[160:163], v[12:15]
	v_mfma_f32_16x16x32_bf16 v[4:7], v[198:201], v[160:163], v[4:7]
	v_mfma_f32_16x16x32_bf16 v[8:11], v[176:179], v[168:171], v[8:11]
	v_mfma_f32_16x16x32_bf16 v[0:3], v[198:201], v[168:171], v[0:3]
	v_mfma_f32_16x16x32_bf16 v[28:31], v[180:183], v[140:143], v[28:31]
	v_mfma_f32_16x16x32_bf16 v[24:27], v[202:205], v[140:143], v[24:27]
	v_mfma_f32_16x16x32_bf16 v[20:23], v[180:183], v[156:159], v[20:23]
	v_mfma_f32_16x16x32_bf16 v[16:19], v[202:205], v[156:159], v[16:19]
	v_mfma_f32_16x16x32_bf16 v[12:15], v[180:183], v[164:167], v[12:15]
	v_mfma_f32_16x16x32_bf16 v[4:7], v[202:205], v[164:167], v[4:7]
	v_mfma_f32_16x16x32_bf16 v[8:11], v[180:183], v[172:175], v[8:11]
	v_mfma_f32_16x16x32_bf16 v[0:3], v[202:205], v[172:175], v[0:3]
	s_barrier
	s_add_u32 s28, s28, 0x10080
	s_addc_u32 s29, s29, 0
	s_mov_b32 m0, s40
	v_lshl_add_u64 v[100:101], s[28:29], 0, v[184:185]
	global_load_lds_dwordx4 v[100:101], off
	v_lshl_add_u64 v[100:101], s[28:29], 0, v[190:191]
	s_mov_b32 m0, s41
	s_nop 0
	global_load_lds_dwordx4 v[100:101], off
	s_add_u32 s22, s22, 0x100
	s_addc_u32 s23, s23, 0
	s_add_u32 s38, s38, 0x100
	s_addc_u32 s39, s39, 0
	s_cmp_ge_i32 s45, s34
	s_mov_b32 s28, s45
	s_cbranch_scc0 .LBB0_112
	s_mov_b32 s66, s4
	s_mov_b32 s67, s5

.LBB0_234:
	v_or_b32_e32 v141, 0x10000, v143
	v_add_u32_e32 v148, 0x10400, v143
	ds_read_b128 v[144:147], v141
	ds_read_b128 v[148:151], v148
	v_add_u32_e32 v141, 0x10800, v143
	v_add_u32_e32 v156, 0x10c00, v143
	ds_read_b128 v[152:155], v141
	ds_read_b128 v[156:159], v156
	s_add_u32 s34, s30, 0xfff00080
	s_addc_u32 s35, s31, -1
	s_cmp_eq_u32 s96, 12
	s_cselect_b32 s37, vcc_lo, s35
	s_cselect_b32 s36, vcc_hi, s34
	s_cselect_b32 s35, s33, s27
	s_cselect_b32 s34, s20, s26
	v_lshl_add_u64 v[190:191], s[30:31], 0, v[136:137]
	s_add_i32 m0, s38, 0xc000
	ds_read_b128 v[160:163], v142
	ds_read_b128 v[164:167], v142 offset:1024
	ds_read_b128 v[168:171], v142 offset:2048
	ds_read_b128 v[172:175], v142 offset:3072
	ds_read_b128 v[176:179], v142 offset:4096
	ds_read_b128 v[180:183], v142 offset:5120
	ds_read_b128 v[186:189], v142 offset:6144
	ds_read_b128 v[194:197], v142 offset:7168
	global_load_lds_dwordx4 v[190:191], off
	v_lshl_add_u64 v[190:191], s[30:31], 0, v[138:139]
	s_add_i32 m0, s38, 0xe000
	s_nop 0
	global_load_lds_dwordx4 v[190:191], off
	v_or_b32_e32 v141, 0x14000, v143
	v_add_u32_e32 v190, 0x14400, v143
	ds_read_b128 v[198:201], v141
	ds_read_b128 v[202:205], v190
	v_add_u32_e32 v141, 0x14800, v143
	v_add_u32_e32 v190, 0x14c00, v143
	ds_read_b128 v[206:209], v141
	ds_read_b128 v[210:213], v190
	s_waitcnt vmcnt(8) lgkmcnt(0)
	s_barrier
	v_mfma_f32_16x16x32_bf16 v[124:127], v[144:147], v[160:163], v[124:127]
	v_mfma_f32_16x16x32_bf16 v[120:123], v[152:155], v[160:163], v[120:123]
	v_mfma_f32_16x16x32_bf16 v[116:119], v[144:147], v[168:171], v[116:119]
	v_mfma_f32_16x16x32_bf16 v[112:115], v[152:155], v[168:171], v[112:115]
	v_mfma_f32_16x16x32_bf16 v[108:111], v[144:147], v[176:179], v[108:111]
	v_mfma_f32_16x16x32_bf16 v[104:107], v[152:155], v[176:179], v[104:107]
	v_mfma_f32_16x16x32_bf16 v[100:103], v[144:147], v[186:189], v[100:103]
	v_mfma_f32_16x16x32_bf16 v[96:99], v[152:155], v[186:189], v[96:99]
	v_mfma_f32_16x16x32_bf16 v[124:127], v[148:151], v[164:167], v[124:127]
	v_mfma_f32_16x16x32_bf16 v[120:123], v[156:159], v[164:167], v[120:123]
	v_mfma_f32_16x16x32_bf16 v[116:119], v[148:151], v[172:175], v[116:119]
	v_mfma_f32_16x16x32_bf16 v[112:115], v[156:159], v[172:175], v[112:115]
	v_mfma_f32_16x16x32_bf16 v[108:111], v[148:151], v[180:183], v[108:111]
	v_mfma_f32_16x16x32_bf16 v[104:107], v[156:159], v[180:183], v[104:107]
	v_mfma_f32_16x16x32_bf16 v[100:103], v[148:151], v[194:197], v[100:103]
	v_mfma_f32_16x16x32_bf16 v[96:99], v[156:159], v[194:197], v[96:99]
	v_mfma_f32_16x16x32_bf16 v[92:95], v[198:201], v[160:163], v[92:95]
	v_mfma_f32_16x16x32_bf16 v[88:91], v[206:209], v[160:163], v[88:91]
	v_mfma_f32_16x16x32_bf16 v[84:87], v[198:201], v[168:171], v[84:87]
	v_mfma_f32_16x16x32_bf16 v[80:83], v[206:209], v[168:171], v[80:83]
	v_mfma_f32_16x16x32_bf16 v[76:79], v[198:201], v[176:179], v[76:79]
	v_mfma_f32_16x16x32_bf16 v[72:75], v[206:209], v[176:179], v[72:75]
	v_mfma_f32_16x16x32_bf16 v[68:71], v[198:201], v[186:189], v[68:71]
	v_mfma_f32_16x16x32_bf16 v[64:67], v[206:209], v[186:189], v[64:67]
	v_mfma_f32_16x16x32_bf16 v[92:95], v[202:205], v[164:167], v[92:95]
	v_mfma_f32_16x16x32_bf16 v[88:91], v[210:213], v[164:167], v[88:91]
	v_mfma_f32_16x16x32_bf16 v[84:87], v[202:205], v[172:175], v[84:87]
	v_mfma_f32_16x16x32_bf16 v[80:83], v[210:213], v[172:175], v[80:83]
	v_mfma_f32_16x16x32_bf16 v[76:79], v[202:205], v[180:183], v[76:79]
	v_mfma_f32_16x16x32_bf16 v[72:75], v[210:213], v[180:183], v[72:75]
	v_mfma_f32_16x16x32_bf16 v[68:71], v[202:205], v[194:197], v[68:71]
	v_mfma_f32_16x16x32_bf16 v[64:67], v[210:213], v[194:197], v[64:67]
	s_barrier
	s_mov_b32 m0, s39
	v_lshl_add_u64 v[190:191], s[34:35], 0, v[132:133]
	global_load_lds_dwordx4 v[190:191], off
	v_lshl_add_u64 v[214:215], s[34:35], 0, v[128:129]
	s_mov_b32 m0, s40
	s_nop 0
	global_load_lds_dwordx4 v[214:215], off
	s_mov_b32 m0, s38
	v_lshl_add_u64 v[216:217], s[36:37], 0, v[134:135]
	ds_read_b128 v[160:163], v142 offset:16384
	ds_read_b128 v[164:167], v142 offset:17408
	ds_read_b128 v[168:171], v142 offset:18432
	ds_read_b128 v[172:175], v142 offset:19456
	ds_read_b128 v[176:179], v142 offset:20480
	ds_read_b128 v[180:183], v142 offset:21504
	ds_read_b128 v[186:189], v142 offset:22528
	ds_read_b128 v[194:197], v142 offset:23552
	global_load_lds_dwordx4 v[216:217], off
	v_lshl_add_u64 v[242:243], s[36:37], 0, v[130:131]
	s_mov_b32 m0, s41
	s_nop 0
	global_load_lds_dwordx4 v[242:243], off
	s_waitcnt vmcnt(6) lgkmcnt(0)
	s_barrier
	v_mfma_f32_16x16x32_bf16 v[60:63], v[144:147], v[160:163], v[60:63]
	v_mfma_f32_16x16x32_bf16 v[56:59], v[152:155], v[160:163], v[56:59]
	v_mfma_f32_16x16x32_bf16 v[52:55], v[144:147], v[168:171], v[52:55]
	v_mfma_f32_16x16x32_bf16 v[48:51], v[152:155], v[168:171], v[48:51]
	v_mfma_f32_16x16x32_bf16 v[44:47], v[144:147], v[176:179], v[44:47]
	v_mfma_f32_16x16x32_bf16 v[40:43], v[152:155], v[176:179], v[40:43]
	v_mfma_f32_16x16x32_bf16 v[36:39], v[144:147], v[186:189], v[36:39]
	v_mfma_f32_16x16x32_bf16 v[32:35], v[152:155], v[186:189], v[32:35]
	v_mfma_f32_16x16x32_bf16 v[60:63], v[148:151], v[164:167], v[60:63]
	v_mfma_f32_16x16x32_bf16 v[56:59], v[156:159], v[164:167], v[56:59]
	v_mfma_f32_16x16x32_bf16 v[52:55], v[148:151], v[172:175], v[52:55]
	v_mfma_f32_16x16x32_bf16 v[48:51], v[156:159], v[172:175], v[48:51]
	v_mfma_f32_16x16x32_bf16 v[44:47], v[148:151], v[180:183], v[44:47]
	v_mfma_f32_16x16x32_bf16 v[40:43], v[156:159], v[180:183], v[40:43]
	v_mfma_f32_16x16x32_bf16 v[36:39], v[148:151], v[194:197], v[36:39]
	v_mfma_f32_16x16x32_bf16 v[32:35], v[156:159], v[194:197], v[32:35]
	v_mfma_f32_16x16x32_bf16 v[28:31], v[198:201], v[160:163], v[28:31]
	v_mfma_f32_16x16x32_bf16 v[24:27], v[206:209], v[160:163], v[24:27]
	v_mfma_f32_16x16x32_bf16 v[20:23], v[198:201], v[168:171], v[20:23]
	v_mfma_f32_16x16x32_bf16 v[16:19], v[206:209], v[168:171], v[16:19]
	v_mfma_f32_16x16x32_bf16 v[12:15], v[198:201], v[176:179], v[12:15]
	v_mfma_f32_16x16x32_bf16 v[8:11], v[206:209], v[176:179], v[8:11]
	v_mfma_f32_16x16x32_bf16 v[4:7], v[198:201], v[186:189], v[4:7]
	v_mfma_f32_16x16x32_bf16 v[0:3], v[206:209], v[186:189], v[0:3]
	v_mfma_f32_16x16x32_bf16 v[28:31], v[202:205], v[164:167], v[28:31]
	v_mfma_f32_16x16x32_bf16 v[24:27], v[210:213], v[164:167], v[24:27]
	v_mfma_f32_16x16x32_bf16 v[20:23], v[202:205], v[172:175], v[20:23]
	v_mfma_f32_16x16x32_bf16 v[16:19], v[210:213], v[172:175], v[16:19]
	v_mfma_f32_16x16x32_bf16 v[12:15], v[202:205], v[180:183], v[12:15]
	v_mfma_f32_16x16x32_bf16 v[8:11], v[210:213], v[180:183], v[8:11]
	v_mfma_f32_16x16x32_bf16 v[4:7], v[202:205], v[194:197], v[4:7]
	v_mfma_f32_16x16x32_bf16 v[0:3], v[210:213], v[194:197], v[0:3]
	s_barrier
	s_add_u32 s66, s34, 0x800000
	s_addc_u32 s67, s35, 0
	s_mov_b32 m0, s42
	v_lshl_add_u64 v[144:145], s[66:67], 0, v[132:133]
	global_load_lds_dwordx4 v[144:145], off
	v_lshl_add_u64 v[144:145], s[66:67], 0, v[128:129]
	s_mov_b32 m0, s43
	s_nop 0
	global_load_lds_dwordx4 v[144:145], off
	v_or_b32_e32 v141, 0x18000, v143
	v_add_u32_e32 v148, 0x18400, v143
	ds_read_b128 v[144:147], v141
	ds_read_b128 v[148:151], v148
	v_add_u32_e32 v141, 0x18800, v143
	v_add_u32_e32 v156, 0x18c00, v143
	ds_read_b128 v[152:155], v141
	ds_read_b128 v[156:159], v156
	s_add_u32 s36, s36, 0x100000
	s_addc_u32 s37, s37, 0
	s_mov_b32 m0, s44
	v_lshl_add_u64 v[198:199], s[36:37], 0, v[134:135]
	ds_read_b128 v[160:163], v142 offset:32768
	ds_read_b128 v[164:167], v142 offset:33792
	ds_read_b128 v[168:171], v142 offset:34816
	ds_read_b128 v[172:175], v142 offset:35840
	ds_read_b128 v[176:179], v142 offset:36864
	ds_read_b128 v[180:183], v142 offset:37888
	ds_read_b128 v[186:189], v142 offset:38912
	ds_read_b128 v[194:197], v142 offset:39936
	global_load_lds_dwordx4 v[198:199], off
	v_lshl_add_u64 v[198:199], s[36:37], 0, v[130:131]
	s_mov_b32 m0, s45
	s_nop 0
	global_load_lds_dwordx4 v[198:199], off
	v_or_b32_e32 v141, 0x1c000, v143
	v_add_u32_e32 v192, 0x1c400, v143
	ds_read_b128 v[198:201], v141
	ds_read_b128 v[202:205], v192
	v_add_u32_e32 v141, 0x1c800, v143
	v_add_u32_e32 v192, 0x1cc00, v143
	ds_read_b128 v[206:209], v141
	ds_read_b128 v[210:213], v192
	s_waitcnt vmcnt(8) lgkmcnt(0)
	s_barrier
	v_mfma_f32_16x16x32_bf16 v[124:127], v[144:147], v[160:163], v[124:127]
	v_mfma_f32_16x16x32_bf16 v[120:123], v[152:155], v[160:163], v[120:123]
	v_mfma_f32_16x16x32_bf16 v[116:119], v[144:147], v[168:171], v[116:119]
	v_mfma_f32_16x16x32_bf16 v[112:115], v[152:155], v[168:171], v[112:115]
	v_mfma_f32_16x16x32_bf16 v[108:111], v[144:147], v[176:179], v[108:111]
	v_mfma_f32_16x16x32_bf16 v[104:107], v[152:155], v[176:179], v[104:107]
	v_mfma_f32_16x16x32_bf16 v[100:103], v[144:147], v[186:189], v[100:103]
	v_mfma_f32_16x16x32_bf16 v[96:99], v[152:155], v[186:189], v[96:99]
	v_mfma_f32_16x16x32_bf16 v[124:127], v[148:151], v[164:167], v[124:127]
	v_mfma_f32_16x16x32_bf16 v[120:123], v[156:159], v[164:167], v[120:123]
	v_mfma_f32_16x16x32_bf16 v[116:119], v[148:151], v[172:175], v[116:119]
	v_mfma_f32_16x16x32_bf16 v[112:115], v[156:159], v[172:175], v[112:115]
	v_mfma_f32_16x16x32_bf16 v[108:111], v[148:151], v[180:183], v[108:111]
	v_mfma_f32_16x16x32_bf16 v[104:107], v[156:159], v[180:183], v[104:107]
	v_mfma_f32_16x16x32_bf16 v[100:103], v[148:151], v[194:197], v[100:103]
	v_mfma_f32_16x16x32_bf16 v[96:99], v[156:159], v[194:197], v[96:99]
	v_mfma_f32_16x16x32_bf16 v[92:95], v[198:201], v[160:163], v[92:95]
	v_mfma_f32_16x16x32_bf16 v[88:91], v[206:209], v[160:163], v[88:91]
	v_mfma_f32_16x16x32_bf16 v[84:87], v[198:201], v[168:171], v[84:87]
	v_mfma_f32_16x16x32_bf16 v[80:83], v[206:209], v[168:171], v[80:83]
	v_mfma_f32_16x16x32_bf16 v[76:79], v[198:201], v[176:179], v[76:79]
	v_mfma_f32_16x16x32_bf16 v[72:75], v[206:209], v[176:179], v[72:75]
	v_mfma_f32_16x16x32_bf16 v[68:71], v[198:201], v[186:189], v[68:71]
	v_mfma_f32_16x16x32_bf16 v[64:67], v[206:209], v[186:189], v[64:67]
	v_mfma_f32_16x16x32_bf16 v[92:95], v[202:205], v[164:167], v[92:95]
	v_mfma_f32_16x16x32_bf16 v[88:91], v[210:213], v[164:167], v[88:91]
	v_mfma_f32_16x16x32_bf16 v[84:87], v[202:205], v[172:175], v[84:87]
	v_mfma_f32_16x16x32_bf16 v[80:83], v[210:213], v[172:175], v[80:83]
	v_mfma_f32_16x16x32_bf16 v[76:79], v[202:205], v[180:183], v[76:79]
	v_mfma_f32_16x16x32_bf16 v[72:75], v[210:213], v[180:183], v[72:75]
	v_mfma_f32_16x16x32_bf16 v[68:71], v[202:205], v[194:197], v[68:71]
	v_mfma_f32_16x16x32_bf16 v[64:67], v[210:213], v[194:197], v[64:67]
	s_barrier
	s_mov_b32 m0, s46
	v_lshl_add_u64 v[190:191], v[190:191], 0, s[24:25]
	global_load_lds_dwordx4 v[190:191], off
	v_lshl_add_u64 v[190:191], v[214:215], 0, s[24:25]
	s_mov_b32 m0, s47
	s_nop 0
	global_load_lds_dwordx4 v[190:191], off
	s_mov_b32 m0, s48
	v_lshl_add_u64 v[190:191], v[216:217], 0, s[24:25]
	ds_read_b128 v[160:163], v142 offset:49152
	ds_read_b128 v[164:167], v142 offset:50176
	ds_read_b128 v[168:171], v142 offset:51200
	ds_read_b128 v[172:175], v142 offset:52224
	ds_read_b128 v[176:179], v142 offset:53248
	ds_read_b128 v[180:183], v142 offset:54272
	ds_read_b128 v[186:189], v142 offset:55296
	ds_read_b128 v[194:197], v142 offset:56320
	global_load_lds_dwordx4 v[190:191], off
	v_lshl_add_u64 v[190:191], v[242:243], 0, s[24:25]
	s_mov_b32 m0, s49
	s_nop 0
	global_load_lds_dwordx4 v[190:191], off
	s_waitcnt vmcnt(6) lgkmcnt(0)
	s_barrier
	v_mfma_f32_16x16x32_bf16 v[60:63], v[144:147], v[160:163], v[60:63]
	v_mfma_f32_16x16x32_bf16 v[56:59], v[152:155], v[160:163], v[56:59]
	v_mfma_f32_16x16x32_bf16 v[52:55], v[144:147], v[168:171], v[52:55]
	v_mfma_f32_16x16x32_bf16 v[48:51], v[152:155], v[168:171], v[48:51]
	v_mfma_f32_16x16x32_bf16 v[44:47], v[144:147], v[176:179], v[44:47]
	v_mfma_f32_16x16x32_bf16 v[40:43], v[152:155], v[176:179], v[40:43]
	v_mfma_f32_16x16x32_bf16 v[36:39], v[144:147], v[186:189], v[36:39]
	v_mfma_f32_16x16x32_bf16 v[32:35], v[152:155], v[186:189], v[32:35]
	v_mfma_f32_16x16x32_bf16 v[60:63], v[148:151], v[164:167], v[60:63]
	v_mfma_f32_16x16x32_bf16 v[56:59], v[156:159], v[164:167], v[56:59]
	v_mfma_f32_16x16x32_bf16 v[52:55], v[148:151], v[172:175], v[52:55]
	v_mfma_f32_16x16x32_bf16 v[48:51], v[156:159], v[172:175], v[48:51]
	v_mfma_f32_16x16x32_bf16 v[44:47], v[148:151], v[180:183], v[44:47]
	v_mfma_f32_16x16x32_bf16 v[40:43], v[156:159], v[180:183], v[40:43]
	v_mfma_f32_16x16x32_bf16 v[36:39], v[148:151], v[194:197], v[36:39]
	v_mfma_f32_16x16x32_bf16 v[32:35], v[156:159], v[194:197], v[32:35]
	v_mfma_f32_16x16x32_bf16 v[28:31], v[198:201], v[160:163], v[28:31]
	v_mfma_f32_16x16x32_bf16 v[24:27], v[206:209], v[160:163], v[24:27]
	v_mfma_f32_16x16x32_bf16 v[20:23], v[198:201], v[168:171], v[20:23]
	v_mfma_f32_16x16x32_bf16 v[16:19], v[206:209], v[168:171], v[16:19]
	v_mfma_f32_16x16x32_bf16 v[12:15], v[198:201], v[176:179], v[12:15]
	v_mfma_f32_16x16x32_bf16 v[8:11], v[206:209], v[176:179], v[8:11]
	v_mfma_f32_16x16x32_bf16 v[4:7], v[198:201], v[186:189], v[4:7]
	v_mfma_f32_16x16x32_bf16 v[0:3], v[206:209], v[186:189], v[0:3]
	v_mfma_f32_16x16x32_bf16 v[28:31], v[202:205], v[164:167], v[28:31]
	v_mfma_f32_16x16x32_bf16 v[24:27], v[210:213], v[164:167], v[24:27]
	v_mfma_f32_16x16x32_bf16 v[20:23], v[202:205], v[172:175], v[20:23]
	v_mfma_f32_16x16x32_bf16 v[16:19], v[210:213], v[172:175], v[16:19]
	v_mfma_f32_16x16x32_bf16 v[12:15], v[202:205], v[180:183], v[12:15]
	v_mfma_f32_16x16x32_bf16 v[8:11], v[210:213], v[180:183], v[8:11]
	v_mfma_f32_16x16x32_bf16 v[4:7], v[202:205], v[194:197], v[4:7]
	v_mfma_f32_16x16x32_bf16 v[0:3], v[210:213], v[194:197], v[0:3]
	s_barrier
	s_add_u32 s34, s34, 0x800080
	s_addc_u32 s35, s35, 0
	s_mov_b32 m0, s50
	v_lshl_add_u64 v[144:145], s[34:35], 0, v[132:133]
	global_load_lds_dwordx4 v[144:145], off
	v_lshl_add_u64 v[144:145], s[34:35], 0, v[128:129]
	s_mov_b32 m0, s51
	s_nop 0
	global_load_lds_dwordx4 v[144:145], off
	s_add_i32 s96, s96, 2
	s_add_u32 s30, s30, 0x100
	s_addc_u32 s31, s31, 0
	s_add_u32 s26, s26, 0x100
	s_addc_u32 s27, s27, 0
	s_cmp_gt_u32 s96, 13
	s_cbranch_scc0 .LBB0_234
	s_lshl_b32 s20, s71, 7
	s_lshl_b32 s26, s56, 4
	s_or_b32 s27, s26, s20
	s_add_i32 s34, s27, s52
	s_lshl_b32 s88, s70, 19
	v_readlane_b32 s72, v253, 16
	s_ashr_i32 s35, s34, 31
	s_lshl_b64 s[30:31], s[88:89], 4
	v_readlane_b32 s74, v253, 18
	v_readlane_b32 s75, v253, 19
	s_add_u32 s27, s74, s30
	s_addc_u32 s30, s75, s31
	s_lshl_b64 s[34:35], s[34:35], 13
	s_add_u32 s31, s27, s34
	s_addc_u32 s33, s30, s35
	s_add_u32 s34, s31, s63
	s_addc_u32 s35, s33, 0
	v_cvt_pk_bf16_f32 v124, v124, v125
	v_cvt_pk_bf16_f32 v125, v126, v127
	v_cvt_pk_bf16_f32 v126, v120, v121
	v_lshl_add_u64 v[120:121], s[34:35], 0, v[184:185]
	s_add_i32 s34, s54, s20
	s_add_i32 s34, s34, s26
	s_ashr_i32 s35, s34, 31
	s_lshl_b64 s[34:35], s[34:35], 13
	s_add_u32 s36, s27, s34
	s_addc_u32 s37, s30, s35
	s_add_u32 s34, s36, s63
	s_addc_u32 s35, s37, 0
	v_cvt_pk_bf16_f32 v116, v116, v117
	v_cvt_pk_bf16_f32 v117, v118, v119
	v_cvt_pk_bf16_f32 v118, v112, v113
	v_lshl_add_u64 v[112:113], s[34:35], 0, v[184:185]
	s_add_i32 s34, s55, s20
	s_add_i32 s34, s34, s26
	s_ashr_i32 s35, s34, 31
	s_lshl_b64 s[34:35], s[34:35], 13
	s_add_u32 s66, s27, s34
	s_addc_u32 s67, s30, s35
	s_add_u32 s34, s66, s63
	s_addc_u32 s35, s67, 0
	v_cvt_pk_bf16_f32 v108, v108, v109
	v_cvt_pk_bf16_f32 v109, v110, v111
	v_cvt_pk_bf16_f32 v110, v104, v105
	v_lshl_add_u64 v[104:105], s[34:35], 0, v[184:185]
	s_add_i32 s34, s58, s20
	s_add_i32 s34, s34, s26
	s_ashr_i32 s35, s34, 31
	s_lshl_b64 s[34:35], s[34:35], 13
	s_add_u32 s70, s27, s34
	s_addc_u32 s71, s30, s35
	s_add_u32 s34, s70, s63
	s_addc_u32 s35, s71, 0
	v_cvt_pk_bf16_f32 v100, v100, v101
	v_cvt_pk_bf16_f32 v101, v102, v103
	v_cvt_pk_bf16_f32 v102, v96, v97
	v_lshl_add_u64 v[96:97], s[34:35], 0, v[184:185]
	s_add_u32 s34, s31, s64
	s_addc_u32 s35, s33, 0
	v_cvt_pk_bf16_f32 v92, v92, v93
	v_cvt_pk_bf16_f32 v93, v94, v95
	v_cvt_pk_bf16_f32 v94, v88, v89
	v_lshl_add_u64 v[88:89], s[34:35], 0, v[184:185]
	s_add_u32 s34, s36, s64
	s_addc_u32 s35, s37, 0
	v_cvt_pk_bf16_f32 v84, v84, v85
	v_cvt_pk_bf16_f32 v85, v86, v87
	v_cvt_pk_bf16_f32 v86, v80, v81
	v_lshl_add_u64 v[80:81], s[34:35], 0, v[184:185]
	s_add_u32 s34, s66, s64
	s_addc_u32 s35, s67, 0
	v_cvt_pk_bf16_f32 v76, v76, v77
	v_cvt_pk_bf16_f32 v77, v78, v79
	v_cvt_pk_bf16_f32 v78, v72, v73
	v_lshl_add_u64 v[72:73], s[34:35], 0, v[184:185]
	s_add_u32 s34, s70, s64
	s_addc_u32 s35, s71, 0
	s_add_i32 s31, s53, s20
	v_cvt_pk_bf16_f32 v68, v68, v69
	v_cvt_pk_bf16_f32 v69, v70, v71
	v_cvt_pk_bf16_f32 v70, v64, v65
	v_lshl_add_u64 v[64:65], s[34:35], 0, v[184:185]
	s_add_i32 s34, s31, s26
	s_ashr_i32 s35, s34, 31
	s_lshl_b64 s[34:35], s[34:35], 13
	s_add_u32 s31, s27, s34
	s_addc_u32 s33, s30, s35
	s_add_u32 s34, s31, s63
	s_addc_u32 s35, s33, 0
	v_cvt_pk_bf16_f32 v60, v60, v61
	v_cvt_pk_bf16_f32 v61, v62, v63
	v_cvt_pk_bf16_f32 v62, v56, v57
	v_lshl_add_u64 v[56:57], s[34:35], 0, v[184:185]
	s_add_i32 s34, s59, s20
	s_add_i32 s34, s34, s26
	s_ashr_i32 s35, s34, 31
	s_lshl_b64 s[34:35], s[34:35], 13
	s_add_u32 s36, s27, s34
	s_addc_u32 s37, s30, s35
	s_add_u32 s34, s36, s63
	s_addc_u32 s35, s37, 0
	v_cvt_pk_bf16_f32 v52, v52, v53
	v_cvt_pk_bf16_f32 v53, v54, v55
	v_cvt_pk_bf16_f32 v54, v48, v49
	v_lshl_add_u64 v[48:49], s[34:35], 0, v[184:185]
	s_add_i32 s34, s60, s20
	s_add_i32 s34, s34, s26
	s_ashr_i32 s35, s34, 31
	s_lshl_b64 s[34:35], s[34:35], 13
	s_add_u32 s66, s27, s34
	s_addc_u32 s67, s30, s35
	s_add_u32 s34, s66, s63
	s_addc_u32 s35, s67, 0
	s_add_i32 s20, s61, s20
	v_cvt_pk_bf16_f32 v44, v44, v45
	v_cvt_pk_bf16_f32 v45, v46, v47
	v_cvt_pk_bf16_f32 v46, v40, v41
	v_lshl_add_u64 v[40:41], s[34:35], 0, v[184:185]
	s_add_i32 s34, s20, s26
	s_ashr_i32 s35, s34, 31
	s_lshl_b64 s[34:35], s[34:35], 13
	s_add_u32 s20, s27, s34
	s_addc_u32 s30, s30, s35
	s_add_u32 s26, s20, s63
	s_addc_u32 s27, s30, 0
	v_cvt_pk_bf16_f32 v36, v36, v37
	v_cvt_pk_bf16_f32 v37, v38, v39
	v_cvt_pk_bf16_f32 v38, v32, v33
	v_lshl_add_u64 v[32:33], s[26:27], 0, v[184:185]
	s_add_u32 s26, s31, s64
	s_addc_u32 s27, s33, 0
	v_cvt_pk_bf16_f32 v28, v28, v29
	v_cvt_pk_bf16_f32 v29, v30, v31
	v_cvt_pk_bf16_f32 v30, v24, v25
	v_lshl_add_u64 v[24:25], s[26:27], 0, v[184:185]
	s_add_u32 s26, s36, s64
	s_addc_u32 s27, s37, 0
	v_cvt_pk_bf16_f32 v20, v20, v21
	v_cvt_pk_bf16_f32 v21, v22, v23
	v_cvt_pk_bf16_f32 v22, v16, v17
	v_lshl_add_u64 v[16:17], s[26:27], 0, v[184:185]
	s_add_u32 s26, s66, s64
	s_addc_u32 s27, s67, 0
	v_cvt_pk_bf16_f32 v12, v12, v13
	v_cvt_pk_bf16_f32 v13, v14, v15
	v_cvt_pk_bf16_f32 v14, v8, v9
	v_lshl_add_u64 v[8:9], s[26:27], 0, v[184:185]
	s_add_u32 s26, s20, s64
	s_addc_u32 s27, s30, 0
	v_mov_b32_e32 v141, v185
	v_cvt_pk_bf16_f32 v4, v4, v5
	v_cvt_pk_bf16_f32 v5, v6, v7
	v_cvt_pk_bf16_f32 v6, v0, v1
	v_lshl_add_u64 v[0:1], s[26:27], 0, v[184:185]
	v_readlane_b32 s78, v253, 22
	v_readlane_b32 s79, v253, 23
	v_lshl_add_u64 v[120:121], v[120:121], 0, v[140:141]
	v_lshl_add_u64 v[112:113], v[112:113], 0, v[140:141]
	v_lshl_add_u64 v[104:105], v[104:105], 0, v[140:141]
	v_lshl_add_u64 v[96:97], v[96:97], 0, v[140:141]
	v_lshl_add_u64 v[88:89], v[88:89], 0, v[140:141]
	v_lshl_add_u64 v[80:81], v[80:81], 0, v[140:141]
	v_lshl_add_u64 v[72:73], v[72:73], 0, v[140:141]
	v_lshl_add_u64 v[64:65], v[64:65], 0, v[140:141]
	v_lshl_add_u64 v[56:57], v[56:57], 0, v[140:141]
	v_lshl_add_u64 v[48:49], v[48:49], 0, v[140:141]
	v_lshl_add_u64 v[40:41], v[40:41], 0, v[140:141]
	v_lshl_add_u64 v[32:33], v[32:33], 0, v[140:141]
	v_lshl_add_u64 v[24:25], v[24:25], 0, v[140:141]
	v_lshl_add_u64 v[16:17], v[16:17], 0, v[140:141]
	v_lshl_add_u64 v[8:9], v[8:9], 0, v[140:141]
	v_lshl_add_u64 v[0:1], v[0:1], 0, v[140:141]
	s_and_b64 vcc, exec, s[0:1]
	s_mov_b32 s71, s65
	s_mov_b32 s70, s68
	s_mov_b32 s56, s69
	v_readlane_b32 s96, v255, 22
	v_cvt_pk_bf16_f32 v127, v122, v123
	v_readlane_b32 s73, v253, 17
	v_readlane_b32 s76, v253, 20
	v_readlane_b32 s77, v253, 21
	v_readlane_b32 s80, v253, 24
	v_readlane_b32 s81, v253, 25
	v_readlane_b32 s82, v253, 26
	v_readlane_b32 s83, v253, 27
	v_readlane_b32 s84, v253, 28
	v_readlane_b32 s85, v253, 29
	v_readlane_b32 s86, v253, 30
	v_readlane_b32 s87, v253, 31
	global_store_dwordx4 v[120:121], v[124:127], off
	v_cvt_pk_bf16_f32 v119, v114, v115
	global_store_dwordx4 v[112:113], v[116:119], off
	v_cvt_pk_bf16_f32 v111, v106, v107
	global_store_dwordx4 v[104:105], v[108:111], off
	v_cvt_pk_bf16_f32 v103, v98, v99
	global_store_dwordx4 v[96:97], v[100:103], off
	v_cvt_pk_bf16_f32 v95, v90, v91
	global_store_dwordx4 v[88:89], v[92:95], off
	v_cvt_pk_bf16_f32 v87, v82, v83
	global_store_dwordx4 v[80:81], v[84:87], off
	v_cvt_pk_bf16_f32 v79, v74, v75
	global_store_dwordx4 v[72:73], v[76:79], off
	v_cvt_pk_bf16_f32 v71, v66, v67
	global_store_dwordx4 v[64:65], v[68:71], off
	v_cvt_pk_bf16_f32 v63, v58, v59
	global_store_dwordx4 v[56:57], v[60:63], off
	v_cvt_pk_bf16_f32 v55, v50, v51
	global_store_dwordx4 v[48:49], v[52:55], off
	v_cvt_pk_bf16_f32 v47, v42, v43
	global_store_dwordx4 v[40:41], v[44:47], off
	v_cvt_pk_bf16_f32 v39, v34, v35
	global_store_dwordx4 v[32:33], v[36:39], off
	v_cvt_pk_bf16_f32 v31, v26, v27
	global_store_dwordx4 v[24:25], v[28:31], off
	v_cvt_pk_bf16_f32 v23, v18, v19
	global_store_dwordx4 v[16:17], v[20:23], off
	v_cvt_pk_bf16_f32 v15, v10, v11
	global_store_dwordx4 v[8:9], v[12:15], off
	v_cvt_pk_bf16_f32 v7, v2, v3
	global_store_dwordx4 v[0:1], v[4:7], off
	s_cbranch_vccz .LBB0_233
	v_readlane_b32 s84, v255, 43
	s_waitcnt vmcnt(0)
	v_readlane_b32 s86, v255, 45
	v_readlane_b32 s87, v255, 46
	v_readlane_b32 s72, v255, 23
	v_readlane_b32 s86, v255, 31
	s_cmpk_gt_u32 s93, 0xff
	v_readlane_b32 s85, v255, 44
	v_readlane_b32 s73, v255, 24
	v_readlane_b32 s74, v255, 25
	v_readlane_b32 s75, v255, 26
	v_readlane_b32 s76, v255, 27
	v_readlane_b32 s77, v255, 28
	v_readlane_b32 s78, v255, 29
	v_readlane_b32 s79, v255, 30
	s_mov_b32 s80, s57
	v_readlane_b32 s93, v255, 34
	v_readlane_b32 s81, v255, 33
	v_readlane_b32 s87, v255, 32
	s_mov_b32 s70, 0xbfb8aa3b
	s_mov_b32 s71, 0x42ce8ed0
	s_cbranch_scc1 .LBB0_238
	s_barrier

.LBB0_245:
	v_or_b32_e32 v144, 0x10000, v143
	v_add_u32_e32 v148, 0x10400, v143
	v_add_u32_e32 v152, 0x10800, v143
	v_add_u32_e32 v156, 0x10c00, v143
	ds_read_b128 v[144:147], v144
	ds_read_b128 v[148:151], v148
	ds_read_b128 v[152:155], v152
	ds_read_b128 v[156:159], v156
	s_add_u32 s34, s30, 0xfffe0080
	s_addc_u32 s35, s31, -1
	s_cmp_eq_u32 s61, 4
	s_cselect_b32 s37, s79, s35
	s_cselect_b32 s36, s78, s34
	s_cselect_b32 s35, s20, s27
	s_cselect_b32 s34, s60, s26
	v_lshl_add_u64 v[190:191], s[30:31], 0, v[138:139]
	s_add_i32 m0, s38, 0xc000
	ds_read_b128 v[160:163], v142
	ds_read_b128 v[164:167], v142 offset:1024
	ds_read_b128 v[168:171], v142 offset:2048
	ds_read_b128 v[172:175], v142 offset:3072
	ds_read_b128 v[176:179], v142 offset:4096
	ds_read_b128 v[180:183], v142 offset:5120
	ds_read_b128 v[186:189], v142 offset:6144
	ds_read_b128 v[194:197], v142 offset:7168
	global_load_lds_dwordx4 v[190:191], off
	v_lshl_add_u64 v[190:191], s[30:31], 0, v[140:141]
	s_add_i32 m0, s38, 0xe000
	s_nop 0
	global_load_lds_dwordx4 v[190:191], off
	v_or_b32_e32 v190, 0x14000, v143
	v_add_u32_e32 v191, 0x14400, v143
	ds_read_b128 v[198:201], v190
	ds_read_b128 v[202:205], v191
	v_add_u32_e32 v190, 0x14800, v143
	v_add_u32_e32 v191, 0x14c00, v143
	ds_read_b128 v[206:209], v190
	ds_read_b128 v[210:213], v191
	s_waitcnt vmcnt(8) lgkmcnt(0)
	s_barrier
	v_mfma_f32_16x16x32_bf16 v[124:127], v[144:147], v[160:163], v[124:127]
	v_mfma_f32_16x16x32_bf16 v[120:123], v[152:155], v[160:163], v[120:123]
	v_mfma_f32_16x16x32_bf16 v[116:119], v[144:147], v[168:171], v[116:119]
	v_mfma_f32_16x16x32_bf16 v[112:115], v[152:155], v[168:171], v[112:115]
	v_mfma_f32_16x16x32_bf16 v[108:111], v[144:147], v[176:179], v[108:111]
	v_mfma_f32_16x16x32_bf16 v[104:107], v[152:155], v[176:179], v[104:107]
	v_mfma_f32_16x16x32_bf16 v[100:103], v[144:147], v[186:189], v[100:103]
	v_mfma_f32_16x16x32_bf16 v[96:99], v[152:155], v[186:189], v[96:99]
	v_mfma_f32_16x16x32_bf16 v[124:127], v[148:151], v[164:167], v[124:127]
	v_mfma_f32_16x16x32_bf16 v[120:123], v[156:159], v[164:167], v[120:123]
	v_mfma_f32_16x16x32_bf16 v[116:119], v[148:151], v[172:175], v[116:119]
	v_mfma_f32_16x16x32_bf16 v[112:115], v[156:159], v[172:175], v[112:115]
	v_mfma_f32_16x16x32_bf16 v[108:111], v[148:151], v[180:183], v[108:111]
	v_mfma_f32_16x16x32_bf16 v[104:107], v[156:159], v[180:183], v[104:107]
	v_mfma_f32_16x16x32_bf16 v[100:103], v[148:151], v[194:197], v[100:103]
	v_mfma_f32_16x16x32_bf16 v[96:99], v[156:159], v[194:197], v[96:99]
	v_mfma_f32_16x16x32_bf16 v[92:95], v[198:201], v[160:163], v[92:95]
	v_mfma_f32_16x16x32_bf16 v[88:91], v[206:209], v[160:163], v[88:91]
	v_mfma_f32_16x16x32_bf16 v[84:87], v[198:201], v[168:171], v[84:87]
	v_mfma_f32_16x16x32_bf16 v[80:83], v[206:209], v[168:171], v[80:83]
	v_mfma_f32_16x16x32_bf16 v[76:79], v[198:201], v[176:179], v[76:79]
	v_mfma_f32_16x16x32_bf16 v[72:75], v[206:209], v[176:179], v[72:75]
	v_mfma_f32_16x16x32_bf16 v[68:71], v[198:201], v[186:189], v[68:71]
	v_mfma_f32_16x16x32_bf16 v[64:67], v[206:209], v[186:189], v[64:67]
	v_mfma_f32_16x16x32_bf16 v[92:95], v[202:205], v[164:167], v[92:95]
	v_mfma_f32_16x16x32_bf16 v[88:91], v[210:213], v[164:167], v[88:91]
	v_mfma_f32_16x16x32_bf16 v[84:87], v[202:205], v[172:175], v[84:87]
	v_mfma_f32_16x16x32_bf16 v[80:83], v[210:213], v[172:175], v[80:83]
	v_mfma_f32_16x16x32_bf16 v[76:79], v[202:205], v[180:183], v[76:79]
	v_mfma_f32_16x16x32_bf16 v[72:75], v[210:213], v[180:183], v[72:75]
	v_mfma_f32_16x16x32_bf16 v[68:71], v[202:205], v[194:197], v[68:71]
	v_mfma_f32_16x16x32_bf16 v[64:67], v[210:213], v[194:197], v[64:67]
	s_barrier
	s_mov_b32 m0, s1
	v_lshl_add_u64 v[190:191], s[34:35], 0, v[184:185]
	global_load_lds_dwordx4 v[190:191], off
	v_lshl_add_u64 v[214:215], s[34:35], 0, v[128:129]
	s_mov_b32 m0, s39
	s_nop 0
	global_load_lds_dwordx4 v[214:215], off
	s_mov_b32 m0, s38
	v_lshl_add_u64 v[216:217], s[36:37], 0, v[132:133]
	ds_read_b128 v[160:163], v142 offset:16384
	ds_read_b128 v[164:167], v142 offset:17408
	ds_read_b128 v[168:171], v142 offset:18432
	ds_read_b128 v[172:175], v142 offset:19456
	ds_read_b128 v[176:179], v142 offset:20480
	ds_read_b128 v[180:183], v142 offset:21504
	ds_read_b128 v[186:189], v142 offset:22528
	ds_read_b128 v[194:197], v142 offset:23552
	global_load_lds_dwordx4 v[216:217], off
	v_lshl_add_u64 v[242:243], s[36:37], 0, v[130:131]
	s_mov_b32 m0, s40
	s_nop 0
	global_load_lds_dwordx4 v[242:243], off
	s_waitcnt vmcnt(6) lgkmcnt(0)
	s_barrier
	v_mfma_f32_16x16x32_bf16 v[60:63], v[144:147], v[160:163], v[60:63]
	v_mfma_f32_16x16x32_bf16 v[56:59], v[152:155], v[160:163], v[56:59]
	v_mfma_f32_16x16x32_bf16 v[52:55], v[144:147], v[168:171], v[52:55]
	v_mfma_f32_16x16x32_bf16 v[48:51], v[152:155], v[168:171], v[48:51]
	v_mfma_f32_16x16x32_bf16 v[44:47], v[144:147], v[176:179], v[44:47]
	v_mfma_f32_16x16x32_bf16 v[40:43], v[152:155], v[176:179], v[40:43]
	v_mfma_f32_16x16x32_bf16 v[36:39], v[144:147], v[186:189], v[36:39]
	v_mfma_f32_16x16x32_bf16 v[32:35], v[152:155], v[186:189], v[32:35]
	v_mfma_f32_16x16x32_bf16 v[60:63], v[148:151], v[164:167], v[60:63]
	v_mfma_f32_16x16x32_bf16 v[56:59], v[156:159], v[164:167], v[56:59]
	v_mfma_f32_16x16x32_bf16 v[52:55], v[148:151], v[172:175], v[52:55]
	v_mfma_f32_16x16x32_bf16 v[48:51], v[156:159], v[172:175], v[48:51]
	v_mfma_f32_16x16x32_bf16 v[44:47], v[148:151], v[180:183], v[44:47]
	v_mfma_f32_16x16x32_bf16 v[40:43], v[156:159], v[180:183], v[40:43]
	v_mfma_f32_16x16x32_bf16 v[36:39], v[148:151], v[194:197], v[36:39]
	v_mfma_f32_16x16x32_bf16 v[32:35], v[156:159], v[194:197], v[32:35]
	v_mfma_f32_16x16x32_bf16 v[28:31], v[198:201], v[160:163], v[28:31]
	v_mfma_f32_16x16x32_bf16 v[24:27], v[206:209], v[160:163], v[24:27]
	v_mfma_f32_16x16x32_bf16 v[20:23], v[198:201], v[168:171], v[20:23]
	v_mfma_f32_16x16x32_bf16 v[16:19], v[206:209], v[168:171], v[16:19]
	v_mfma_f32_16x16x32_bf16 v[12:15], v[198:201], v[176:179], v[12:15]
	v_mfma_f32_16x16x32_bf16 v[8:11], v[206:209], v[176:179], v[8:11]
	v_mfma_f32_16x16x32_bf16 v[4:7], v[198:201], v[186:189], v[4:7]
	v_mfma_f32_16x16x32_bf16 v[0:3], v[206:209], v[186:189], v[0:3]
	v_mfma_f32_16x16x32_bf16 v[28:31], v[202:205], v[164:167], v[28:31]
	v_mfma_f32_16x16x32_bf16 v[24:27], v[210:213], v[164:167], v[24:27]
	v_mfma_f32_16x16x32_bf16 v[20:23], v[202:205], v[172:175], v[20:23]
	v_mfma_f32_16x16x32_bf16 v[16:19], v[210:213], v[172:175], v[16:19]
	v_mfma_f32_16x16x32_bf16 v[12:15], v[202:205], v[180:183], v[12:15]
	v_mfma_f32_16x16x32_bf16 v[8:11], v[210:213], v[180:183], v[8:11]
	v_mfma_f32_16x16x32_bf16 v[4:7], v[202:205], v[194:197], v[4:7]
	v_mfma_f32_16x16x32_bf16 v[0:3], v[210:213], v[194:197], v[0:3]
	s_barrier
	s_add_u32 s62, s34, 0x100000
	s_addc_u32 s63, s35, 0
	s_mov_b32 m0, s41
	v_lshl_add_u64 v[144:145], s[62:63], 0, v[184:185]
	global_load_lds_dwordx4 v[144:145], off
	v_lshl_add_u64 v[144:145], s[62:63], 0, v[128:129]
	s_mov_b32 m0, s42
	s_nop 0
	global_load_lds_dwordx4 v[144:145], off
	v_or_b32_e32 v144, 0x18000, v143
	v_add_u32_e32 v148, 0x18400, v143
	v_add_u32_e32 v152, 0x18800, v143
	v_add_u32_e32 v156, 0x18c00, v143
	ds_read_b128 v[144:147], v144
	ds_read_b128 v[148:151], v148
	ds_read_b128 v[152:155], v152
	ds_read_b128 v[156:159], v156
	s_add_u32 s36, s36, 0x20000
	s_addc_u32 s37, s37, 0
	s_mov_b32 m0, s43
	v_lshl_add_u64 v[198:199], s[36:37], 0, v[132:133]
	ds_read_b128 v[160:163], v142 offset:32768
	ds_read_b128 v[164:167], v142 offset:33792
	ds_read_b128 v[168:171], v142 offset:34816
	ds_read_b128 v[172:175], v142 offset:35840
	ds_read_b128 v[176:179], v142 offset:36864
	ds_read_b128 v[180:183], v142 offset:37888
	ds_read_b128 v[186:189], v142 offset:38912
	ds_read_b128 v[194:197], v142 offset:39936
	global_load_lds_dwordx4 v[198:199], off
	v_lshl_add_u64 v[198:199], s[36:37], 0, v[130:131]
	s_mov_b32 m0, s44
	s_nop 0
	global_load_lds_dwordx4 v[198:199], off
	v_or_b32_e32 v192, 0x1c000, v143
	v_add_u32_e32 v202, 0x1c400, v143
	ds_read_b128 v[198:201], v192
	ds_read_b128 v[202:205], v202
	v_add_u32_e32 v192, 0x1c800, v143
	v_add_u32_e32 v210, 0x1cc00, v143
	ds_read_b128 v[206:209], v192
	ds_read_b128 v[210:213], v210
	s_waitcnt vmcnt(8) lgkmcnt(0)
	s_barrier
	v_mfma_f32_16x16x32_bf16 v[124:127], v[144:147], v[160:163], v[124:127]
	v_mfma_f32_16x16x32_bf16 v[120:123], v[152:155], v[160:163], v[120:123]
	v_mfma_f32_16x16x32_bf16 v[116:119], v[144:147], v[168:171], v[116:119]
	v_mfma_f32_16x16x32_bf16 v[112:115], v[152:155], v[168:171], v[112:115]
	v_mfma_f32_16x16x32_bf16 v[108:111], v[144:147], v[176:179], v[108:111]
	v_mfma_f32_16x16x32_bf16 v[104:107], v[152:155], v[176:179], v[104:107]
	v_mfma_f32_16x16x32_bf16 v[100:103], v[144:147], v[186:189], v[100:103]
	v_mfma_f32_16x16x32_bf16 v[96:99], v[152:155], v[186:189], v[96:99]
	v_mfma_f32_16x16x32_bf16 v[124:127], v[148:151], v[164:167], v[124:127]
	v_mfma_f32_16x16x32_bf16 v[120:123], v[156:159], v[164:167], v[120:123]
	v_mfma_f32_16x16x32_bf16 v[116:119], v[148:151], v[172:175], v[116:119]
	v_mfma_f32_16x16x32_bf16 v[112:115], v[156:159], v[172:175], v[112:115]
	v_mfma_f32_16x16x32_bf16 v[108:111], v[148:151], v[180:183], v[108:111]
	v_mfma_f32_16x16x32_bf16 v[104:107], v[156:159], v[180:183], v[104:107]
	v_mfma_f32_16x16x32_bf16 v[100:103], v[148:151], v[194:197], v[100:103]
	v_mfma_f32_16x16x32_bf16 v[96:99], v[156:159], v[194:197], v[96:99]
	v_mfma_f32_16x16x32_bf16 v[92:95], v[198:201], v[160:163], v[92:95]
	v_mfma_f32_16x16x32_bf16 v[88:91], v[206:209], v[160:163], v[88:91]
	v_mfma_f32_16x16x32_bf16 v[84:87], v[198:201], v[168:171], v[84:87]
	v_mfma_f32_16x16x32_bf16 v[80:83], v[206:209], v[168:171], v[80:83]
	v_mfma_f32_16x16x32_bf16 v[76:79], v[198:201], v[176:179], v[76:79]
	v_mfma_f32_16x16x32_bf16 v[72:75], v[206:209], v[176:179], v[72:75]
	v_mfma_f32_16x16x32_bf16 v[68:71], v[198:201], v[186:189], v[68:71]
	v_mfma_f32_16x16x32_bf16 v[64:67], v[206:209], v[186:189], v[64:67]
	v_mfma_f32_16x16x32_bf16 v[92:95], v[202:205], v[164:167], v[92:95]
	v_mfma_f32_16x16x32_bf16 v[88:91], v[210:213], v[164:167], v[88:91]
	v_mfma_f32_16x16x32_bf16 v[84:87], v[202:205], v[172:175], v[84:87]
	v_mfma_f32_16x16x32_bf16 v[80:83], v[210:213], v[172:175], v[80:83]
	v_mfma_f32_16x16x32_bf16 v[76:79], v[202:205], v[180:183], v[76:79]
	v_mfma_f32_16x16x32_bf16 v[72:75], v[210:213], v[180:183], v[72:75]
	v_mfma_f32_16x16x32_bf16 v[68:71], v[202:205], v[194:197], v[68:71]
	v_mfma_f32_16x16x32_bf16 v[64:67], v[210:213], v[194:197], v[64:67]
	s_barrier
	s_mov_b32 m0, s45
	v_lshl_add_u64 v[190:191], v[190:191], 0, s[24:25]
	global_load_lds_dwordx4 v[190:191], off
	v_lshl_add_u64 v[190:191], v[214:215], 0, s[24:25]
	s_mov_b32 m0, s46
	s_nop 0
	global_load_lds_dwordx4 v[190:191], off
	s_mov_b32 m0, s47
	v_lshl_add_u64 v[190:191], v[216:217], 0, s[24:25]
	ds_read_b128 v[160:163], v142 offset:49152
	ds_read_b128 v[164:167], v142 offset:50176
	ds_read_b128 v[168:171], v142 offset:51200
	ds_read_b128 v[172:175], v142 offset:52224
	ds_read_b128 v[176:179], v142 offset:53248
	ds_read_b128 v[180:183], v142 offset:54272
	ds_read_b128 v[186:189], v142 offset:55296
	ds_read_b128 v[194:197], v142 offset:56320
	global_load_lds_dwordx4 v[190:191], off
	v_lshl_add_u64 v[190:191], v[242:243], 0, s[24:25]
	s_mov_b32 m0, s48
	s_nop 0
	global_load_lds_dwordx4 v[190:191], off
	s_waitcnt vmcnt(6) lgkmcnt(0)
	s_barrier
	v_mfma_f32_16x16x32_bf16 v[60:63], v[144:147], v[160:163], v[60:63]
	v_mfma_f32_16x16x32_bf16 v[56:59], v[152:155], v[160:163], v[56:59]
	v_mfma_f32_16x16x32_bf16 v[52:55], v[144:147], v[168:171], v[52:55]
	v_mfma_f32_16x16x32_bf16 v[48:51], v[152:155], v[168:171], v[48:51]
	v_mfma_f32_16x16x32_bf16 v[44:47], v[144:147], v[176:179], v[44:47]
	v_mfma_f32_16x16x32_bf16 v[40:43], v[152:155], v[176:179], v[40:43]
	v_mfma_f32_16x16x32_bf16 v[36:39], v[144:147], v[186:189], v[36:39]
	v_mfma_f32_16x16x32_bf16 v[32:35], v[152:155], v[186:189], v[32:35]
	v_mfma_f32_16x16x32_bf16 v[60:63], v[148:151], v[164:167], v[60:63]
	v_mfma_f32_16x16x32_bf16 v[56:59], v[156:159], v[164:167], v[56:59]
	v_mfma_f32_16x16x32_bf16 v[52:55], v[148:151], v[172:175], v[52:55]
	v_mfma_f32_16x16x32_bf16 v[48:51], v[156:159], v[172:175], v[48:51]
	v_mfma_f32_16x16x32_bf16 v[44:47], v[148:151], v[180:183], v[44:47]
	v_mfma_f32_16x16x32_bf16 v[40:43], v[156:159], v[180:183], v[40:43]
	v_mfma_f32_16x16x32_bf16 v[36:39], v[148:151], v[194:197], v[36:39]
	v_mfma_f32_16x16x32_bf16 v[32:35], v[156:159], v[194:197], v[32:35]
	v_mfma_f32_16x16x32_bf16 v[28:31], v[198:201], v[160:163], v[28:31]
	v_mfma_f32_16x16x32_bf16 v[24:27], v[206:209], v[160:163], v[24:27]
	v_mfma_f32_16x16x32_bf16 v[20:23], v[198:201], v[168:171], v[20:23]
	v_mfma_f32_16x16x32_bf16 v[16:19], v[206:209], v[168:171], v[16:19]
	v_mfma_f32_16x16x32_bf16 v[12:15], v[198:201], v[176:179], v[12:15]
	v_mfma_f32_16x16x32_bf16 v[8:11], v[206:209], v[176:179], v[8:11]
	v_mfma_f32_16x16x32_bf16 v[4:7], v[198:201], v[186:189], v[4:7]
	v_mfma_f32_16x16x32_bf16 v[0:3], v[206:209], v[186:189], v[0:3]
	v_mfma_f32_16x16x32_bf16 v[28:31], v[202:205], v[164:167], v[28:31]
	v_mfma_f32_16x16x32_bf16 v[24:27], v[210:213], v[164:167], v[24:27]
	v_mfma_f32_16x16x32_bf16 v[20:23], v[202:205], v[172:175], v[20:23]
	v_mfma_f32_16x16x32_bf16 v[16:19], v[210:213], v[172:175], v[16:19]
	v_mfma_f32_16x16x32_bf16 v[12:15], v[202:205], v[180:183], v[12:15]
	v_mfma_f32_16x16x32_bf16 v[8:11], v[210:213], v[180:183], v[8:11]
	v_mfma_f32_16x16x32_bf16 v[4:7], v[202:205], v[194:197], v[4:7]
	v_mfma_f32_16x16x32_bf16 v[0:3], v[210:213], v[194:197], v[0:3]
	s_barrier
	s_add_u32 s34, s34, 0x100080
	s_addc_u32 s35, s35, 0
	s_mov_b32 m0, s49
	v_lshl_add_u64 v[144:145], s[34:35], 0, v[184:185]
	global_load_lds_dwordx4 v[144:145], off
	v_lshl_add_u64 v[144:145], s[34:35], 0, v[128:129]
	s_mov_b32 m0, s50
	s_nop 0
	global_load_lds_dwordx4 v[144:145], off
	s_add_i32 s61, s61, 2
	s_add_u32 s30, s30, 0x100
	s_addc_u32 s31, s31, 0
	s_add_u32 s26, s26, 0x100
	s_addc_u32 s27, s27, 0
	s_cmp_gt_u32 s61, 5
	s_cbranch_scc0 .LBB0_245
	s_lshl_b32 s20, s59, 4
	s_add_i32 s30, s20, s51
	s_add_i32 s34, s52, s20
	s_add_i32 s36, s53, s20
	s_ashr_i32 s31, s30, 31
	s_ashr_i32 s35, s34, 31
	s_ashr_i32 s37, s36, 31
	s_lshl_b64 s[26:27], s[30:31], 13
	s_lshl_b64 s[34:35], s[34:35], 13
	s_lshl_b64 s[36:37], s[36:37], 13
	v_cvt_pk_bf16_f32 v124, v124, v125
	v_cvt_pk_bf16_f32 v125, v126, v127
	v_cvt_pk_bf16_f32 v126, v120, v121
	v_lshl_add_u64 v[120:121], v[134:135], 0, s[26:27]
	v_cvt_pk_bf16_f32 v116, v116, v117
	v_cvt_pk_bf16_f32 v117, v118, v119
	v_cvt_pk_bf16_f32 v118, v112, v113
	v_lshl_add_u64 v[112:113], v[134:135], 0, s[34:35]
	v_cvt_pk_bf16_f32 v108, v108, v109
	v_cvt_pk_bf16_f32 v109, v110, v111
	v_cvt_pk_bf16_f32 v110, v104, v105
	v_lshl_add_u64 v[104:105], v[134:135], 0, s[36:37]
	s_add_i32 s60, s54, s20
	v_cvt_pk_bf16_f32 v92, v92, v93
	v_cvt_pk_bf16_f32 v93, v94, v95
	v_cvt_pk_bf16_f32 v94, v88, v89
	v_lshl_add_u64 v[88:89], v[136:137], 0, s[26:27]
	v_cvt_pk_bf16_f32 v84, v84, v85
	v_cvt_pk_bf16_f32 v85, v86, v87
	v_cvt_pk_bf16_f32 v86, v80, v81
	v_lshl_add_u64 v[80:81], v[136:137], 0, s[34:35]
	v_cvt_pk_bf16_f32 v76, v76, v77
	v_cvt_pk_bf16_f32 v77, v78, v79
	v_cvt_pk_bf16_f32 v78, v72, v73
	v_lshl_add_u64 v[72:73], v[136:137], 0, s[36:37]
	s_add_i32 s26, s30, 8
	s_add_i32 s34, s30, 9
	s_add_i32 s36, s30, 10
	s_add_i32 s30, s30, 11
	s_ashr_i32 s61, s60, 31
	s_ashr_i32 s27, s26, 31
	s_ashr_i32 s35, s34, 31
	s_ashr_i32 s37, s36, 31
	s_ashr_i32 s31, s30, 31
	s_lshl_b64 s[60:61], s[60:61], 13
	s_lshl_b64 s[26:27], s[26:27], 13
	s_lshl_b64 s[34:35], s[34:35], 13
	s_lshl_b64 s[36:37], s[36:37], 13
	s_lshl_b64 s[30:31], s[30:31], 13
	v_cvt_pk_bf16_f32 v100, v100, v101
	v_cvt_pk_bf16_f32 v101, v102, v103
	v_cvt_pk_bf16_f32 v102, v96, v97
	v_lshl_add_u64 v[96:97], v[134:135], 0, s[60:61]
	v_cvt_pk_bf16_f32 v68, v68, v69
	v_cvt_pk_bf16_f32 v69, v70, v71
	v_cvt_pk_bf16_f32 v70, v64, v65
	v_lshl_add_u64 v[64:65], v[136:137], 0, s[60:61]
	v_cvt_pk_bf16_f32 v60, v60, v61
	v_cvt_pk_bf16_f32 v61, v62, v63
	v_cvt_pk_bf16_f32 v62, v56, v57
	v_lshl_add_u64 v[56:57], v[134:135], 0, s[26:27]
	v_cvt_pk_bf16_f32 v52, v52, v53
	v_cvt_pk_bf16_f32 v53, v54, v55
	v_cvt_pk_bf16_f32 v54, v48, v49
	v_lshl_add_u64 v[48:49], v[134:135], 0, s[34:35]
	v_cvt_pk_bf16_f32 v44, v44, v45
	v_cvt_pk_bf16_f32 v45, v46, v47
	v_cvt_pk_bf16_f32 v46, v40, v41
	v_lshl_add_u64 v[40:41], v[134:135], 0, s[36:37]
	v_cvt_pk_bf16_f32 v36, v36, v37
	v_cvt_pk_bf16_f32 v37, v38, v39
	v_cvt_pk_bf16_f32 v38, v32, v33
	v_lshl_add_u64 v[32:33], v[134:135], 0, s[30:31]
	v_cvt_pk_bf16_f32 v28, v28, v29
	v_cvt_pk_bf16_f32 v29, v30, v31
	v_cvt_pk_bf16_f32 v30, v24, v25
	v_lshl_add_u64 v[24:25], v[136:137], 0, s[26:27]
	v_cvt_pk_bf16_f32 v20, v20, v21
	v_cvt_pk_bf16_f32 v21, v22, v23
	v_cvt_pk_bf16_f32 v22, v16, v17
	v_lshl_add_u64 v[16:17], v[136:137], 0, s[34:35]
	v_cvt_pk_bf16_f32 v12, v12, v13
	v_cvt_pk_bf16_f32 v13, v14, v15
	v_cvt_pk_bf16_f32 v14, v8, v9
	v_lshl_add_u64 v[8:9], v[136:137], 0, s[36:37]
	v_cvt_pk_bf16_f32 v4, v4, v5
	v_cvt_pk_bf16_f32 v5, v6, v7
	v_cvt_pk_bf16_f32 v6, v0, v1
	v_lshl_add_u64 v[0:1], v[136:137], 0, s[30:31]
	s_and_b64 vcc, exec, s[28:29]
	s_mov_b32 s59, s58
	v_cvt_pk_bf16_f32 v127, v122, v123
	global_store_dwordx4 v[120:121], v[124:127], off
	v_cvt_pk_bf16_f32 v119, v114, v115
	global_store_dwordx4 v[112:113], v[116:119], off
	v_cvt_pk_bf16_f32 v111, v106, v107
	global_store_dwordx4 v[104:105], v[108:111], off
	v_cvt_pk_bf16_f32 v103, v98, v99
	global_store_dwordx4 v[96:97], v[100:103], off
	v_cvt_pk_bf16_f32 v95, v90, v91
	global_store_dwordx4 v[88:89], v[92:95], off
	v_cvt_pk_bf16_f32 v87, v82, v83
	global_store_dwordx4 v[80:81], v[84:87], off
	v_cvt_pk_bf16_f32 v79, v74, v75
	global_store_dwordx4 v[72:73], v[76:79], off
	v_cvt_pk_bf16_f32 v71, v66, v67
	global_store_dwordx4 v[64:65], v[68:71], off
	v_cvt_pk_bf16_f32 v63, v58, v59
	global_store_dwordx4 v[56:57], v[60:63], off
	v_cvt_pk_bf16_f32 v55, v50, v51
	global_store_dwordx4 v[48:49], v[52:55], off
	v_cvt_pk_bf16_f32 v47, v42, v43
	global_store_dwordx4 v[40:41], v[44:47], off
	v_cvt_pk_bf16_f32 v39, v34, v35
	global_store_dwordx4 v[32:33], v[36:39], off
	v_cvt_pk_bf16_f32 v31, v26, v27
	global_store_dwordx4 v[24:25], v[28:31], off
	v_cvt_pk_bf16_f32 v23, v18, v19
	global_store_dwordx4 v[16:17], v[20:23], off
	v_cvt_pk_bf16_f32 v15, v10, v11
	global_store_dwordx4 v[8:9], v[12:15], off
	v_cvt_pk_bf16_f32 v7, v2, v3
	global_store_dwordx4 v[0:1], v[4:7], off
	s_cbranch_vccz .LBB0_244
	s_waitcnt vmcnt(0)
	s_cmpk_gt_u32 s33, 0xff
	s_cbranch_scc1 .LBB0_249
	s_barrier

.LBB0_299:
	v_or_b32_e32 v128, 0x10000, v143
	v_add_u32_e32 v152, 0x10400, v143
	v_add_u32_e32 v157, 0x10800, v143
	v_add_u32_e32 v162, 0x10c00, v143
	ds_read_b128 v[128:131], v128
	ds_read_b128 v[152:155], v152
	ds_read_b128 v[158:161], v157
	ds_read_b128 v[162:165], v162
	s_add_u32 s28, s0, 0xfffc0080
	s_addc_u32 s29, s1, -1
	s_cmp_eq_u32 s27, 12
	s_cselect_b32 s31, s20, s29
	s_cselect_b32 s30, s34, s28
	s_cselect_b32 s29, s35, s26
	s_cselect_b32 s28, s36, s37
	v_lshl_add_u64 v[182:183], s[0:1], 0, v[148:149]
	s_add_i32 m0, s58, 0xc000
	ds_read_b128 v[166:169], v141
	ds_read_b128 v[170:173], v141 offset:1024
	ds_read_b128 v[174:177], v141 offset:2048
	ds_read_b128 v[178:181], v141 offset:3072
	ds_read_b128 v[186:189], v141 offset:4096
	ds_read_b128 v[194:197], v141 offset:5120
	ds_read_b128 v[198:201], v141 offset:6144
	ds_read_b128 v[202:205], v141 offset:7168
	global_load_lds_dwordx4 v[182:183], off
	v_lshl_add_u64 v[182:183], s[0:1], 0, v[150:151]
	s_add_i32 m0, s58, 0xe000
	s_nop 0
	global_load_lds_dwordx4 v[182:183], off
	v_or_b32_e32 v157, 0x14000, v143
	v_add_u32_e32 v182, 0x14400, v143
	ds_read_b128 v[206:209], v157
	ds_read_b128 v[210:213], v182
	v_add_u32_e32 v157, 0x14800, v143
	v_add_u32_e32 v182, 0x14c00, v143
	ds_read_b128 v[214:217], v157
	ds_read_b128 v[242:245], v182
	s_waitcnt vmcnt(8) lgkmcnt(0)
	s_barrier
	v_mfma_f32_16x16x32_bf16 v[124:127], v[128:131], v[166:169], v[124:127]
	v_mfma_f32_16x16x32_bf16 v[120:123], v[158:161], v[166:169], v[120:123]
	v_mfma_f32_16x16x32_bf16 v[116:119], v[128:131], v[174:177], v[116:119]
	v_mfma_f32_16x16x32_bf16 v[112:115], v[158:161], v[174:177], v[112:115]
	v_mfma_f32_16x16x32_bf16 v[108:111], v[128:131], v[186:189], v[108:111]
	v_mfma_f32_16x16x32_bf16 v[104:107], v[158:161], v[186:189], v[104:107]
	v_mfma_f32_16x16x32_bf16 v[100:103], v[128:131], v[198:201], v[100:103]
	v_mfma_f32_16x16x32_bf16 v[96:99], v[158:161], v[198:201], v[96:99]
	v_mfma_f32_16x16x32_bf16 v[124:127], v[152:155], v[170:173], v[124:127]
	v_mfma_f32_16x16x32_bf16 v[120:123], v[162:165], v[170:173], v[120:123]
	v_mfma_f32_16x16x32_bf16 v[116:119], v[152:155], v[178:181], v[116:119]
	v_mfma_f32_16x16x32_bf16 v[112:115], v[162:165], v[178:181], v[112:115]
	v_mfma_f32_16x16x32_bf16 v[108:111], v[152:155], v[194:197], v[108:111]
	v_mfma_f32_16x16x32_bf16 v[104:107], v[162:165], v[194:197], v[104:107]
	v_mfma_f32_16x16x32_bf16 v[100:103], v[152:155], v[202:205], v[100:103]
	v_mfma_f32_16x16x32_bf16 v[96:99], v[162:165], v[202:205], v[96:99]
	v_mfma_f32_16x16x32_bf16 v[92:95], v[206:209], v[166:169], v[92:95]
	v_mfma_f32_16x16x32_bf16 v[88:91], v[214:217], v[166:169], v[88:91]
	v_mfma_f32_16x16x32_bf16 v[84:87], v[206:209], v[174:177], v[84:87]
	v_mfma_f32_16x16x32_bf16 v[80:83], v[214:217], v[174:177], v[80:83]
	v_mfma_f32_16x16x32_bf16 v[76:79], v[206:209], v[186:189], v[76:79]
	v_mfma_f32_16x16x32_bf16 v[72:75], v[214:217], v[186:189], v[72:75]
	v_mfma_f32_16x16x32_bf16 v[68:71], v[206:209], v[198:201], v[68:71]
	v_mfma_f32_16x16x32_bf16 v[64:67], v[214:217], v[198:201], v[64:67]
	v_mfma_f32_16x16x32_bf16 v[92:95], v[210:213], v[170:173], v[92:95]
	v_mfma_f32_16x16x32_bf16 v[88:91], v[242:245], v[170:173], v[88:91]
	v_mfma_f32_16x16x32_bf16 v[84:87], v[210:213], v[178:181], v[84:87]
	v_mfma_f32_16x16x32_bf16 v[80:83], v[242:245], v[178:181], v[80:83]
	v_mfma_f32_16x16x32_bf16 v[76:79], v[210:213], v[194:197], v[76:79]
	v_mfma_f32_16x16x32_bf16 v[72:75], v[242:245], v[194:197], v[72:75]
	v_mfma_f32_16x16x32_bf16 v[68:71], v[210:213], v[202:205], v[68:71]
	v_mfma_f32_16x16x32_bf16 v[64:67], v[242:245], v[202:205], v[64:67]
	s_barrier
	s_mov_b32 m0, s39
	v_lshl_add_u64 v[182:183], s[28:29], 0, v[134:135]
	global_load_lds_dwordx4 v[182:183], off
	v_lshl_add_u64 v[190:191], s[28:29], 0, v[138:139]
	s_mov_b32 m0, s59
	s_nop 0
	global_load_lds_dwordx4 v[190:191], off
	s_mov_b32 m0, s58
	v_lshl_add_u64 v[246:247], s[30:31], 0, v[132:133]
	ds_read_b128 v[166:169], v141 offset:16384
	ds_read_b128 v[170:173], v141 offset:17408
	ds_read_b128 v[174:177], v141 offset:18432
	ds_read_b128 v[178:181], v141 offset:19456
	ds_read_b128 v[186:189], v141 offset:20480
	ds_read_b128 v[194:197], v141 offset:21504
	ds_read_b128 v[198:201], v141 offset:22528
	ds_read_b128 v[202:205], v141 offset:23552
	global_load_lds_dwordx4 v[246:247], off
	v_lshl_add_u64 v[248:249], s[30:31], 0, v[136:137]
	s_mov_b32 m0, s60
	s_nop 0
	global_load_lds_dwordx4 v[248:249], off
	s_waitcnt vmcnt(6) lgkmcnt(0)
	s_barrier
	v_mfma_f32_16x16x32_bf16 v[60:63], v[128:131], v[166:169], v[60:63]
	v_mfma_f32_16x16x32_bf16 v[56:59], v[158:161], v[166:169], v[56:59]
	v_mfma_f32_16x16x32_bf16 v[52:55], v[128:131], v[174:177], v[52:55]
	v_mfma_f32_16x16x32_bf16 v[48:51], v[158:161], v[174:177], v[48:51]
	v_mfma_f32_16x16x32_bf16 v[44:47], v[128:131], v[186:189], v[44:47]
	v_mfma_f32_16x16x32_bf16 v[40:43], v[158:161], v[186:189], v[40:43]
	v_mfma_f32_16x16x32_bf16 v[36:39], v[128:131], v[198:201], v[36:39]
	v_mfma_f32_16x16x32_bf16 v[32:35], v[158:161], v[198:201], v[32:35]
	v_mfma_f32_16x16x32_bf16 v[60:63], v[152:155], v[170:173], v[60:63]
	v_mfma_f32_16x16x32_bf16 v[56:59], v[162:165], v[170:173], v[56:59]
	v_mfma_f32_16x16x32_bf16 v[52:55], v[152:155], v[178:181], v[52:55]
	v_mfma_f32_16x16x32_bf16 v[48:51], v[162:165], v[178:181], v[48:51]
	v_mfma_f32_16x16x32_bf16 v[44:47], v[152:155], v[194:197], v[44:47]
	v_mfma_f32_16x16x32_bf16 v[40:43], v[162:165], v[194:197], v[40:43]
	v_mfma_f32_16x16x32_bf16 v[36:39], v[152:155], v[202:205], v[36:39]
	v_mfma_f32_16x16x32_bf16 v[32:35], v[162:165], v[202:205], v[32:35]
	v_mfma_f32_16x16x32_bf16 v[28:31], v[206:209], v[166:169], v[28:31]
	v_mfma_f32_16x16x32_bf16 v[24:27], v[214:217], v[166:169], v[24:27]
	v_mfma_f32_16x16x32_bf16 v[20:23], v[206:209], v[174:177], v[20:23]
	v_mfma_f32_16x16x32_bf16 v[16:19], v[214:217], v[174:177], v[16:19]
	v_mfma_f32_16x16x32_bf16 v[12:15], v[206:209], v[186:189], v[12:15]
	v_mfma_f32_16x16x32_bf16 v[8:11], v[214:217], v[186:189], v[8:11]
	v_mfma_f32_16x16x32_bf16 v[4:7], v[206:209], v[198:201], v[4:7]
	v_mfma_f32_16x16x32_bf16 v[0:3], v[214:217], v[198:201], v[0:3]
	v_mfma_f32_16x16x32_bf16 v[28:31], v[210:213], v[170:173], v[28:31]
	v_mfma_f32_16x16x32_bf16 v[24:27], v[242:245], v[170:173], v[24:27]
	v_mfma_f32_16x16x32_bf16 v[20:23], v[210:213], v[178:181], v[20:23]
	v_mfma_f32_16x16x32_bf16 v[16:19], v[242:245], v[178:181], v[16:19]
	v_mfma_f32_16x16x32_bf16 v[12:15], v[210:213], v[194:197], v[12:15]
	v_mfma_f32_16x16x32_bf16 v[8:11], v[242:245], v[194:197], v[8:11]
	v_mfma_f32_16x16x32_bf16 v[4:7], v[210:213], v[202:205], v[4:7]
	v_mfma_f32_16x16x32_bf16 v[0:3], v[242:245], v[202:205], v[0:3]
	s_barrier
	s_add_u32 s46, s28, 0x40000
	s_addc_u32 s47, s29, 0
	s_mov_b32 m0, s61
	v_lshl_add_u64 v[128:129], s[46:47], 0, v[134:135]
	global_load_lds_dwordx4 v[128:129], off
	v_lshl_add_u64 v[128:129], s[46:47], 0, v[138:139]
	s_mov_b32 m0, s62
	s_nop 0
	global_load_lds_dwordx4 v[128:129], off
	v_or_b32_e32 v128, 0x18000, v143
	v_add_u32_e32 v152, 0x18400, v143
	v_add_u32_e32 v157, 0x18800, v143
	v_add_u32_e32 v162, 0x18c00, v143
	ds_read_b128 v[128:131], v128
	ds_read_b128 v[152:155], v152
	ds_read_b128 v[158:161], v157
	ds_read_b128 v[162:165], v162
	s_add_u32 s30, s30, 0x40000
	s_addc_u32 s31, s31, 0
	s_mov_b32 m0, s63
	v_lshl_add_u64 v[206:207], s[30:31], 0, v[132:133]
	ds_read_b128 v[166:169], v141 offset:32768
	ds_read_b128 v[170:173], v141 offset:33792
	ds_read_b128 v[174:177], v141 offset:34816
	ds_read_b128 v[178:181], v141 offset:35840
	ds_read_b128 v[186:189], v141 offset:36864
	ds_read_b128 v[194:197], v141 offset:37888
	ds_read_b128 v[198:201], v141 offset:38912
	ds_read_b128 v[202:205], v141 offset:39936
	global_load_lds_dwordx4 v[206:207], off
	v_lshl_add_u64 v[206:207], s[30:31], 0, v[136:137]
	s_mov_b32 m0, s64
	s_nop 0
	global_load_lds_dwordx4 v[206:207], off
	v_or_b32_e32 v157, 0x1c000, v143
	v_add_u32_e32 v184, 0x1c400, v143
	ds_read_b128 v[206:209], v157
	ds_read_b128 v[210:213], v184
	v_add_u32_e32 v157, 0x1c800, v143
	v_add_u32_e32 v184, 0x1cc00, v143
	ds_read_b128 v[214:217], v157
	ds_read_b128 v[242:245], v184
	s_waitcnt vmcnt(8) lgkmcnt(0)
	s_barrier
	v_mfma_f32_16x16x32_bf16 v[124:127], v[128:131], v[166:169], v[124:127]
	v_mfma_f32_16x16x32_bf16 v[120:123], v[158:161], v[166:169], v[120:123]
	v_mfma_f32_16x16x32_bf16 v[116:119], v[128:131], v[174:177], v[116:119]
	v_mfma_f32_16x16x32_bf16 v[112:115], v[158:161], v[174:177], v[112:115]
	v_mfma_f32_16x16x32_bf16 v[108:111], v[128:131], v[186:189], v[108:111]
	v_mfma_f32_16x16x32_bf16 v[104:107], v[158:161], v[186:189], v[104:107]
	v_mfma_f32_16x16x32_bf16 v[100:103], v[128:131], v[198:201], v[100:103]
	v_mfma_f32_16x16x32_bf16 v[96:99], v[158:161], v[198:201], v[96:99]
	v_mfma_f32_16x16x32_bf16 v[124:127], v[152:155], v[170:173], v[124:127]
	v_mfma_f32_16x16x32_bf16 v[120:123], v[162:165], v[170:173], v[120:123]
	v_mfma_f32_16x16x32_bf16 v[116:119], v[152:155], v[178:181], v[116:119]
	v_mfma_f32_16x16x32_bf16 v[112:115], v[162:165], v[178:181], v[112:115]
	v_mfma_f32_16x16x32_bf16 v[108:111], v[152:155], v[194:197], v[108:111]
	v_mfma_f32_16x16x32_bf16 v[104:107], v[162:165], v[194:197], v[104:107]
	v_mfma_f32_16x16x32_bf16 v[100:103], v[152:155], v[202:205], v[100:103]
	v_mfma_f32_16x16x32_bf16 v[96:99], v[162:165], v[202:205], v[96:99]
	v_mfma_f32_16x16x32_bf16 v[92:95], v[206:209], v[166:169], v[92:95]
	v_mfma_f32_16x16x32_bf16 v[88:91], v[214:217], v[166:169], v[88:91]
	v_mfma_f32_16x16x32_bf16 v[84:87], v[206:209], v[174:177], v[84:87]
	v_mfma_f32_16x16x32_bf16 v[80:83], v[214:217], v[174:177], v[80:83]
	v_mfma_f32_16x16x32_bf16 v[76:79], v[206:209], v[186:189], v[76:79]
	v_mfma_f32_16x16x32_bf16 v[72:75], v[214:217], v[186:189], v[72:75]
	v_mfma_f32_16x16x32_bf16 v[68:71], v[206:209], v[198:201], v[68:71]
	v_mfma_f32_16x16x32_bf16 v[64:67], v[214:217], v[198:201], v[64:67]
	v_mfma_f32_16x16x32_bf16 v[92:95], v[210:213], v[170:173], v[92:95]
	v_mfma_f32_16x16x32_bf16 v[88:91], v[242:245], v[170:173], v[88:91]
	v_mfma_f32_16x16x32_bf16 v[84:87], v[210:213], v[178:181], v[84:87]
	v_mfma_f32_16x16x32_bf16 v[80:83], v[242:245], v[178:181], v[80:83]
	v_mfma_f32_16x16x32_bf16 v[76:79], v[210:213], v[194:197], v[76:79]
	v_mfma_f32_16x16x32_bf16 v[72:75], v[242:245], v[194:197], v[72:75]
	v_mfma_f32_16x16x32_bf16 v[68:71], v[210:213], v[202:205], v[68:71]
	v_mfma_f32_16x16x32_bf16 v[64:67], v[242:245], v[202:205], v[64:67]
	s_barrier
	s_mov_b32 m0, s68
	v_lshl_add_u64 v[182:183], v[182:183], 0, s[24:25]
	global_load_lds_dwordx4 v[182:183], off
	v_lshl_add_u64 v[182:183], v[190:191], 0, s[24:25]
	s_mov_b32 m0, s69
	s_nop 0
	global_load_lds_dwordx4 v[182:183], off
	s_mov_b32 m0, s70
	v_lshl_add_u64 v[182:183], v[246:247], 0, s[24:25]
	ds_read_b128 v[166:169], v141 offset:49152
	ds_read_b128 v[170:173], v141 offset:50176
	ds_read_b128 v[174:177], v141 offset:51200
	ds_read_b128 v[178:181], v141 offset:52224
	ds_read_b128 v[186:189], v141 offset:53248
	ds_read_b128 v[194:197], v141 offset:54272
	ds_read_b128 v[198:201], v141 offset:55296
	ds_read_b128 v[202:205], v141 offset:56320
	global_load_lds_dwordx4 v[182:183], off
	v_lshl_add_u64 v[182:183], v[248:249], 0, s[24:25]
	s_mov_b32 m0, s71
	s_nop 0
	global_load_lds_dwordx4 v[182:183], off
	s_waitcnt vmcnt(6) lgkmcnt(0)
	s_barrier
	v_mfma_f32_16x16x32_bf16 v[60:63], v[128:131], v[166:169], v[60:63]
	v_mfma_f32_16x16x32_bf16 v[56:59], v[158:161], v[166:169], v[56:59]
	v_mfma_f32_16x16x32_bf16 v[52:55], v[128:131], v[174:177], v[52:55]
	v_mfma_f32_16x16x32_bf16 v[48:51], v[158:161], v[174:177], v[48:51]
	v_mfma_f32_16x16x32_bf16 v[44:47], v[128:131], v[186:189], v[44:47]
	v_mfma_f32_16x16x32_bf16 v[40:43], v[158:161], v[186:189], v[40:43]
	v_mfma_f32_16x16x32_bf16 v[36:39], v[128:131], v[198:201], v[36:39]
	v_mfma_f32_16x16x32_bf16 v[32:35], v[158:161], v[198:201], v[32:35]
	v_mfma_f32_16x16x32_bf16 v[60:63], v[152:155], v[170:173], v[60:63]
	v_mfma_f32_16x16x32_bf16 v[56:59], v[162:165], v[170:173], v[56:59]
	v_mfma_f32_16x16x32_bf16 v[52:55], v[152:155], v[178:181], v[52:55]
	v_mfma_f32_16x16x32_bf16 v[48:51], v[162:165], v[178:181], v[48:51]
	v_mfma_f32_16x16x32_bf16 v[44:47], v[152:155], v[194:197], v[44:47]
	v_mfma_f32_16x16x32_bf16 v[40:43], v[162:165], v[194:197], v[40:43]
	v_mfma_f32_16x16x32_bf16 v[36:39], v[152:155], v[202:205], v[36:39]
	v_mfma_f32_16x16x32_bf16 v[32:35], v[162:165], v[202:205], v[32:35]
	v_mfma_f32_16x16x32_bf16 v[28:31], v[206:209], v[166:169], v[28:31]
	v_mfma_f32_16x16x32_bf16 v[24:27], v[214:217], v[166:169], v[24:27]
	v_mfma_f32_16x16x32_bf16 v[20:23], v[206:209], v[174:177], v[20:23]
	v_mfma_f32_16x16x32_bf16 v[16:19], v[214:217], v[174:177], v[16:19]
	v_mfma_f32_16x16x32_bf16 v[12:15], v[206:209], v[186:189], v[12:15]
	v_mfma_f32_16x16x32_bf16 v[8:11], v[214:217], v[186:189], v[8:11]
	v_mfma_f32_16x16x32_bf16 v[4:7], v[206:209], v[198:201], v[4:7]
	v_mfma_f32_16x16x32_bf16 v[0:3], v[214:217], v[198:201], v[0:3]
	v_mfma_f32_16x16x32_bf16 v[28:31], v[210:213], v[170:173], v[28:31]
	v_mfma_f32_16x16x32_bf16 v[24:27], v[242:245], v[170:173], v[24:27]
	v_mfma_f32_16x16x32_bf16 v[20:23], v[210:213], v[178:181], v[20:23]
	v_mfma_f32_16x16x32_bf16 v[16:19], v[242:245], v[178:181], v[16:19]
	v_mfma_f32_16x16x32_bf16 v[12:15], v[210:213], v[194:197], v[12:15]
	v_mfma_f32_16x16x32_bf16 v[8:11], v[242:245], v[194:197], v[8:11]
	v_mfma_f32_16x16x32_bf16 v[4:7], v[210:213], v[202:205], v[4:7]
	v_mfma_f32_16x16x32_bf16 v[0:3], v[242:245], v[202:205], v[0:3]
	s_barrier
	s_add_u32 s28, s28, 0x40080
	s_addc_u32 s29, s29, 0
	s_mov_b32 m0, s52
	v_lshl_add_u64 v[128:129], s[28:29], 0, v[134:135]
	global_load_lds_dwordx4 v[128:129], off
	v_lshl_add_u64 v[128:129], s[28:29], 0, v[138:139]
	s_mov_b32 m0, s50
	s_nop 0
	global_load_lds_dwordx4 v[128:129], off
	s_add_i32 s27, s27, 2
	s_add_u32 s0, s0, 0x100
	s_addc_u32 s1, s1, 0
	s_add_u32 s37, s37, 0x100
	s_addc_u32 s26, s26, 0
	s_cmp_gt_u32 s27, 13
	s_cbranch_scc0 .LBB0_299
	s_lshl_b32 s20, s53, 8
	s_add_i32 s20, s20, s66
	s_lshl_b32 s46, s38, 8
	s_cmp_lg_u32 s33, 0
	v_or_b32_e32 v154, s20, v140
	v_or_b32_e32 v152, s46, v144
	s_cselect_b64 s[28:29], -1, 0
	s_movk_i32 s33, 0x3fff
	s_and_b64 vcc, exec, s[28:29]
	v_and_b32_e32 v157, 0xcf, v154
	v_cmp_lt_i32_e64 s[0:1], s33, v152
	s_cbranch_vccz .LBB0_306
	s_ashr_i32 s30, s20, 8
	v_cvt_pk_bf16_f32 v128, v124, v125
	v_cvt_pk_bf16_f32 v129, v126, v127
	v_cvt_pk_bf16_f32 v130, v120, v121
	v_cvt_pk_bf16_f32 v131, v122, v123
	s_and_saveexec_b64 s[26:27], s[0:1]
	s_xor_b64 s[0:1], exec, s[26:27]
	s_cbranch_execz .LBB0_303
	s_add_i32 s26, s46, 0xffffc000
	s_lshr_b32 s26, s26, 7
	v_lshl_add_u32 v184, v157, 4, s26
	s_ashr_i32 s31, s30, 31
	v_lshl_add_u64 v[158:159], v[184:185], 0, s[30:31]
	v_lshlrev_b64 v[158:159], 9, v[158:159]
	v_lshl_add_u64 v[158:159], v[146:147], 0, v[158:159]
	global_store_dwordx4 v[158:159], v[128:131], off
